# all GEMM K-loops MFMA order variant n_chain
# speedup vs baseline: 1.0177x; 1.0177x over previous
; #define PG8_STAGE(bufoff, gbase, voff) do { _Pragma("unroll") for (int _i = 0; _i < 2; ++_i) \
;         __builtin_amdgcn_global_load_lds((const unsigned*)((const char*)(gbase) + (voff)[_i]), (PG8_LAS unsigned*)(lds + (bufoff) + ldsw + _i * 8192), 16, 0, 0); } while (0)
; #define PG8_LDA(dst, b, h) do { _Pragma("unroll") for (int m = 0; m < 4; ++m) _Pragma("unroll") for (int k = 0; k < 2; ++k) dst[m][k] = *(const PG8_LAS bf16x8*)(lds + PG8_SA(b, h) + aoff + m * 2048 + k * 1024); } while (0)
; #define PG8_LDB(dst, b, h) do { _Pragma("unroll") for (int n = 0; n < 2; ++n) _Pragma("unroll") for (int k = 0; k < 2; ++k) dst[n][k] = *(const PG8_LAS bf16x8*)(lds + PG8_SB(b, h) + boff + n * 2048 + k * 1024); } while (0)
; #define PG8_MMA(ai, bj, At, Bt) do { __builtin_amdgcn_s_setprio(1); _Pragma("unroll") for (int m = 0; m < 4; ++m) _Pragma("unroll") for (int n = 0; n < 2; ++n) _Pragma("unroll") for (int k = 0; k < 2; ++k) \
;         acc[ai][bj][m][n] = __builtin_amdgcn_mfma_f32_16x16x32_bf16(Bt[n][k], At[m][k], acc[ai][bj][m][n], 0, 0, 0); __builtin_amdgcn_s_setprio(0); } while (0)
; #define PG8_WAIT_V(n) asm volatile("s_waitcnt vmcnt(" #n ")" ::: "memory")
; #define PG8_WAIT_L(n) asm volatile("s_waitcnt lgkmcnt(" #n ")" ::: "memory")
; #define PG8_BAR __builtin_amdgcn_s_barrier()
; #define PG8_SCHED __builtin_amdgcn_sched_barrier(0)
; template <class Epi, class Sched, bool ALIGN_EPI = false, bool SP2 = false>
; __device__ __forceinline__ void gemm_phase(PG8_LAS unsigned char* lds, const Gemm g, const Sched& S, const Epi& E) {
;     ...
;             const char* a2 = last ? nA : cA + (size_t)(t + 2) * kstep; const char* b2 = last ? nB : cB + (size_t)(t + 2) * kstep;
;             const char* a3 = a2 + kstep; const char* b3 = b2 + kstep;
;             if (last && has_next) S.a_ready(nxt);
;             if constexpr (SP2) {
;             PG8_LDB(B0, 0, 0); PG8_LDB(B1, 0, 1); PG8_SCHED; PG8_LDA(At, 0, 0); PG8_STAGE(PG8_SA(1, 1), a1 + hstep, voffA);
;             PG8_WAIT_V(8); PG8_WAIT_L(0); PG8_BAR; PG8_MMA(0, 0, At, B0); PG8_MMA(0, 1, At, B1); PG8_BAR; PG8_SCHED;
;             PG8_LDA(At, 0, 1); PG8_STAGE(PG8_SB(0, 0), b2, voffB); PG8_STAGE(PG8_SB(0, 1), b2 + hstep, voffB); PG8_STAGE(PG8_SA(0, 0), a2, voffA);
;             PG8_WAIT_V(8); PG8_WAIT_L(0); PG8_BAR; PG8_MMA(1, 0, At, B0); PG8_MMA(1, 1, At, B1); PG8_BAR; PG8_SCHED;
.LBB11_228:
	ds_read_b128 v[152:155], v149
	ds_read_b128 v[156:159], v149 offset:1024
	ds_read_b128 v[160:163], v149 offset:2048
	ds_read_b128 v[164:167], v149 offset:3072
	ds_read_b128 v[168:171], v150
	ds_read_b128 v[172:175], v150 offset:1024
	ds_read_b128 v[176:179], v150 offset:2048
	ds_read_b128 v[180:183], v150 offset:3072
	s_add_u32 s30, s28, 0xfff80080
	s_addc_u32 s31, s29, -1
	s_cmp_eq_u32 s61, 28
	s_cselect_b32 s35, s21, s31
	s_cselect_b32 s34, s57, s30
	s_cselect_b32 s31, s19, s60
	s_cselect_b32 s30, s58, s59
	v_lshl_add_u64 v[144:145], s[28:29], 0, v[140:141]
	s_add_i32 m0, s27, 0xc000
	ds_read_b128 v[184:187], v151
	ds_read_b128 v[188:191], v151 offset:1024
	ds_read_b128 v[192:195], v151 offset:2048
	ds_read_b128 v[196:199], v151 offset:3072
	ds_read_b128 v[200:203], v151 offset:4096
	ds_read_b128 v[204:207], v151 offset:5120
	ds_read_b128 v[210:213], v151 offset:6144
	ds_read_b128 v[214:217], v151 offset:7168
	global_load_lds_dwordx4 v[144:145], off
	v_lshl_add_u64 v[144:145], s[28:29], 0, v[142:143]
	s_add_i32 m0, s27, 0xe000
	s_nop 0
	global_load_lds_dwordx4 v[144:145], off
	s_waitcnt vmcnt(8)
	s_waitcnt lgkmcnt(0)
	s_barrier
	s_setprio 1
	s_waitcnt lgkmcnt(0)
	v_mfma_f32_16x16x32_bf16 v[126:129], v[152:155], v[184:187], v[126:129]
	v_mfma_f32_16x16x32_bf16 v[126:129], v[156:159], v[188:191], v[126:129]
	v_mfma_f32_16x16x32_bf16 v[118:121], v[152:155], v[192:195], v[118:121]
	v_mfma_f32_16x16x32_bf16 v[118:121], v[156:159], v[196:199], v[118:121]
	v_mfma_f32_16x16x32_bf16 v[102:105], v[152:155], v[200:203], v[102:105]
	v_mfma_f32_16x16x32_bf16 v[102:105], v[156:159], v[204:207], v[102:105]
	v_mfma_f32_16x16x32_bf16 v[86:89], v[152:155], v[210:213], v[86:89]
	v_mfma_f32_16x16x32_bf16 v[86:89], v[156:159], v[214:217], v[86:89]
	v_mfma_f32_16x16x32_bf16 v[122:125], v[160:163], v[184:187], v[122:125]
	v_mfma_f32_16x16x32_bf16 v[122:125], v[164:167], v[188:191], v[122:125]
	v_mfma_f32_16x16x32_bf16 v[110:113], v[160:163], v[192:195], v[110:113]
	v_mfma_f32_16x16x32_bf16 v[110:113], v[164:167], v[196:199], v[110:113]
	v_mfma_f32_16x16x32_bf16 v[94:97], v[160:163], v[200:203], v[94:97]
	v_mfma_f32_16x16x32_bf16 v[94:97], v[164:167], v[204:207], v[94:97]
	v_mfma_f32_16x16x32_bf16 v[78:81], v[160:163], v[210:213], v[78:81]
	v_mfma_f32_16x16x32_bf16 v[78:81], v[164:167], v[214:217], v[78:81]
	s_setprio 0
	s_setprio 1
	v_mfma_f32_16x16x32_bf16 v[114:117], v[168:171], v[184:187], v[114:117]
	v_mfma_f32_16x16x32_bf16 v[114:117], v[172:175], v[188:191], v[114:117]
	v_mfma_f32_16x16x32_bf16 v[98:101], v[168:171], v[192:195], v[98:101]
	v_mfma_f32_16x16x32_bf16 v[98:101], v[172:175], v[196:199], v[98:101]
	v_mfma_f32_16x16x32_bf16 v[82:85], v[168:171], v[200:203], v[82:85]
	v_mfma_f32_16x16x32_bf16 v[82:85], v[172:175], v[204:207], v[82:85]
	v_mfma_f32_16x16x32_bf16 v[70:73], v[168:171], v[210:213], v[70:73]
	v_mfma_f32_16x16x32_bf16 v[70:73], v[172:175], v[214:217], v[70:73]
	v_mfma_f32_16x16x32_bf16 v[106:109], v[176:179], v[184:187], v[106:109]
	v_mfma_f32_16x16x32_bf16 v[106:109], v[180:183], v[188:191], v[106:109]
	v_mfma_f32_16x16x32_bf16 v[90:93], v[176:179], v[192:195], v[90:93]
	v_mfma_f32_16x16x32_bf16 v[90:93], v[180:183], v[196:199], v[90:93]
	v_mfma_f32_16x16x32_bf16 v[74:77], v[176:179], v[200:203], v[74:77]
	v_mfma_f32_16x16x32_bf16 v[74:77], v[180:183], v[204:207], v[74:77]
	v_mfma_f32_16x16x32_bf16 v[66:69], v[176:179], v[210:213], v[66:69]
	v_mfma_f32_16x16x32_bf16 v[66:69], v[180:183], v[214:217], v[66:69]
	s_setprio 0
	s_barrier
	s_add_i32 s62, s50, s37
	v_lshl_add_u64 v[144:145], s[30:31], 0, v[134:135]
	s_mov_b32 m0, s62
	ds_read_b128 v[184:187], v151 offset:16384
	ds_read_b128 v[188:191], v151 offset:17408
	ds_read_b128 v[192:195], v151 offset:18432
	ds_read_b128 v[196:199], v151 offset:19456
	ds_read_b128 v[200:203], v151 offset:20480
	ds_read_b128 v[204:207], v151 offset:21504
	ds_read_b128 v[210:213], v151 offset:22528
	ds_read_b128 v[214:217], v151 offset:23552
	global_load_lds_dwordx4 v[144:145], off
	s_add_i32 m0, s62, 0x2000
	s_add_u32 s62, s30, 0x80000
	v_lshl_add_u64 v[218:219], s[30:31], 0, v[130:131]
	s_addc_u32 s63, s31, 0
	s_add_i32 s64, s51, s37
	global_load_lds_dwordx4 v[218:219], off
	v_lshl_add_u64 v[220:221], s[62:63], 0, v[134:135]
	s_mov_b32 m0, s64
	v_lshl_add_u64 v[222:223], s[34:35], 0, v[132:133]
	global_load_lds_dwordx4 v[220:221], off
	v_lshl_add_u64 v[220:221], s[62:63], 0, v[130:131]
	s_add_i32 m0, s64, 0x2000
	s_nop 0
	global_load_lds_dwordx4 v[220:221], off
	v_lshl_add_u64 v[220:221], s[34:35], 0, v[136:137]
	s_mov_b32 m0, s27
	s_nop 0
	global_load_lds_dwordx4 v[220:221], off
	s_mov_b32 m0, s39
	s_nop 0
	global_load_lds_dwordx4 v[222:223], off
	s_waitcnt vmcnt(8)
	s_waitcnt lgkmcnt(0)
	s_barrier
; #define PG8_STAGE(bufoff, gbase, voff) do { _Pragma("unroll") for (int _i = 0; _i < 2; ++_i) \
;         __builtin_amdgcn_global_load_lds((const unsigned*)((const char*)(gbase) + (voff)[_i]), (PG8_LAS unsigned*)(lds + (bufoff) + ldsw + _i * 8192), 16, 0, 0); } while (0)
; #define PG8_LDA(dst, b, h) do { _Pragma("unroll") for (int m = 0; m < 4; ++m) _Pragma("unroll") for (int k = 0; k < 2; ++k) dst[m][k] = *(const PG8_LAS bf16x8*)(lds + PG8_SA(b, h) + aoff + m * 2048 + k * 1024); } while (0)
; #define PG8_LDB(dst, b, h) do { _Pragma("unroll") for (int n = 0; n < 2; ++n) _Pragma("unroll") for (int k = 0; k < 2; ++k) dst[n][k] = *(const PG8_LAS bf16x8*)(lds + PG8_SB(b, h) + boff + n * 2048 + k * 1024); } while (0)
; #define PG8_MMA(ai, bj, At, Bt) do { __builtin_amdgcn_s_setprio(1); _Pragma("unroll") for (int m = 0; m < 4; ++m) _Pragma("unroll") for (int n = 0; n < 2; ++n) _Pragma("unroll") for (int k = 0; k < 2; ++k) \
;         acc[ai][bj][m][n] = __builtin_amdgcn_mfma_f32_16x16x32_bf16(Bt[n][k], At[m][k], acc[ai][bj][m][n], 0, 0, 0); __builtin_amdgcn_s_setprio(0); } while (0)
; #define PG8_WAIT_V(n) asm volatile("s_waitcnt vmcnt(" #n ")" ::: "memory")
; #define PG8_WAIT_L(n) asm volatile("s_waitcnt lgkmcnt(" #n ")" ::: "memory")
; #define PG8_BAR __builtin_amdgcn_s_barrier()
; #define PG8_SCHED __builtin_amdgcn_sched_barrier(0)
; template <class Epi, class Sched, bool ALIGN_EPI = false, bool SP2 = false>
; __device__ __forceinline__ void gemm_phase(PG8_LAS unsigned char* lds, const Gemm g, const Sched& S, const Epi& E) {
;     ...
;             PG8_WAIT_V(8); PG8_WAIT_L(0); PG8_BAR; PG8_MMA(1, 0, At, B0); PG8_MMA(1, 1, At, B1); PG8_BAR; PG8_SCHED;
;             PG8_LDB(B0, 1, 0); PG8_LDB(B1, 1, 1); PG8_SCHED; PG8_LDA(At, 1, 0); PG8_STAGE(PG8_SA(0, 1), a2 + hstep, voffA);
;             PG8_WAIT_V(8); PG8_WAIT_L(0); PG8_BAR; PG8_MMA(0, 0, At, B0); PG8_MMA(0, 1, At, B1); PG8_BAR; PG8_SCHED;
	s_setprio 1
	s_waitcnt lgkmcnt(0)
	v_mfma_f32_16x16x32_bf16 v[62:65], v[152:155], v[184:187], v[62:65]
	v_mfma_f32_16x16x32_bf16 v[62:65], v[156:159], v[188:191], v[62:65]
	v_mfma_f32_16x16x32_bf16 v[54:57], v[152:155], v[192:195], v[54:57]
	v_mfma_f32_16x16x32_bf16 v[54:57], v[156:159], v[196:199], v[54:57]
	v_mfma_f32_16x16x32_bf16 v[38:41], v[152:155], v[200:203], v[38:41]
	v_mfma_f32_16x16x32_bf16 v[38:41], v[156:159], v[204:207], v[38:41]
	v_mfma_f32_16x16x32_bf16 v[22:25], v[152:155], v[210:213], v[22:25]
	v_mfma_f32_16x16x32_bf16 v[22:25], v[156:159], v[214:217], v[22:25]
	v_mfma_f32_16x16x32_bf16 v[58:61], v[160:163], v[184:187], v[58:61]
	v_mfma_f32_16x16x32_bf16 v[58:61], v[164:167], v[188:191], v[58:61]
	v_mfma_f32_16x16x32_bf16 v[46:49], v[160:163], v[192:195], v[46:49]
	v_mfma_f32_16x16x32_bf16 v[46:49], v[164:167], v[196:199], v[46:49]
	v_mfma_f32_16x16x32_bf16 v[30:33], v[160:163], v[200:203], v[30:33]
	v_mfma_f32_16x16x32_bf16 v[30:33], v[164:167], v[204:207], v[30:33]
	v_mfma_f32_16x16x32_bf16 v[14:17], v[160:163], v[210:213], v[14:17]
	v_mfma_f32_16x16x32_bf16 v[14:17], v[164:167], v[214:217], v[14:17]
	s_setprio 0
	s_setprio 1
	v_mfma_f32_16x16x32_bf16 v[50:53], v[168:171], v[184:187], v[50:53]
	v_mfma_f32_16x16x32_bf16 v[50:53], v[172:175], v[188:191], v[50:53]
	v_mfma_f32_16x16x32_bf16 v[34:37], v[168:171], v[192:195], v[34:37]
	v_mfma_f32_16x16x32_bf16 v[34:37], v[172:175], v[196:199], v[34:37]
	v_mfma_f32_16x16x32_bf16 v[18:21], v[168:171], v[200:203], v[18:21]
	v_mfma_f32_16x16x32_bf16 v[18:21], v[172:175], v[204:207], v[18:21]
	v_mfma_f32_16x16x32_bf16 v[6:9], v[168:171], v[210:213], v[6:9]
	v_mfma_f32_16x16x32_bf16 v[6:9], v[172:175], v[214:217], v[6:9]
	v_mfma_f32_16x16x32_bf16 v[42:45], v[176:179], v[184:187], v[42:45]
	v_mfma_f32_16x16x32_bf16 v[42:45], v[180:183], v[188:191], v[42:45]
	v_mfma_f32_16x16x32_bf16 v[26:29], v[176:179], v[192:195], v[26:29]
	v_mfma_f32_16x16x32_bf16 v[26:29], v[180:183], v[196:199], v[26:29]
	v_mfma_f32_16x16x32_bf16 v[10:13], v[176:179], v[200:203], v[10:13]
	v_mfma_f32_16x16x32_bf16 v[10:13], v[180:183], v[204:207], v[10:13]
	v_mfma_f32_16x16x32_bf16 v[2:5], v[176:179], v[210:213], v[2:5]
	v_mfma_f32_16x16x32_bf16 v[2:5], v[180:183], v[214:217], v[2:5]
	s_setprio 0
	s_barrier
	s_add_i32 s62, 0, 0x18000
	s_add_i32 s63, 0, 0x1c000
	v_add_u32_e32 v164, s62, v147
	v_add_u32_e32 v180, s63, v147
	ds_read_b128 v[152:155], v164
	ds_read_b128 v[156:159], v164 offset:1024
	ds_read_b128 v[160:163], v164 offset:2048
	ds_read_b128 v[164:167], v164 offset:3072
	ds_read_b128 v[168:171], v180
	ds_read_b128 v[172:175], v180 offset:1024
	ds_read_b128 v[176:179], v180 offset:2048
	ds_read_b128 v[180:183], v180 offset:3072
	s_add_u32 s34, s34, 0x80000
	s_addc_u32 s35, s35, 0
	s_mov_b32 m0, s40
	v_lshl_add_u64 v[224:225], s[34:35], 0, v[136:137]
	ds_read_b128 v[184:187], v151 offset:32768
	ds_read_b128 v[188:191], v151 offset:33792
	ds_read_b128 v[192:195], v151 offset:34816
	ds_read_b128 v[196:199], v151 offset:35840
	ds_read_b128 v[200:203], v151 offset:36864
	ds_read_b128 v[204:207], v151 offset:37888
	ds_read_b128 v[210:213], v151 offset:38912
	ds_read_b128 v[214:217], v151 offset:39936
	global_load_lds_dwordx4 v[224:225], off
	v_lshl_add_u64 v[224:225], s[34:35], 0, v[132:133]
	s_mov_b32 m0, s41
	s_nop 0
	global_load_lds_dwordx4 v[224:225], off
	s_waitcnt vmcnt(8)
	s_waitcnt lgkmcnt(0)
	s_barrier
	s_setprio 1
	s_waitcnt lgkmcnt(0)
	v_mfma_f32_16x16x32_bf16 v[126:129], v[152:155], v[184:187], v[126:129]
	v_mfma_f32_16x16x32_bf16 v[126:129], v[156:159], v[188:191], v[126:129]
	v_mfma_f32_16x16x32_bf16 v[118:121], v[152:155], v[192:195], v[118:121]
	v_mfma_f32_16x16x32_bf16 v[118:121], v[156:159], v[196:199], v[118:121]
	v_mfma_f32_16x16x32_bf16 v[102:105], v[152:155], v[200:203], v[102:105]
	v_mfma_f32_16x16x32_bf16 v[102:105], v[156:159], v[204:207], v[102:105]
	v_mfma_f32_16x16x32_bf16 v[86:89], v[152:155], v[210:213], v[86:89]
	v_mfma_f32_16x16x32_bf16 v[86:89], v[156:159], v[214:217], v[86:89]
	v_mfma_f32_16x16x32_bf16 v[122:125], v[160:163], v[184:187], v[122:125]
	v_mfma_f32_16x16x32_bf16 v[122:125], v[164:167], v[188:191], v[122:125]
	v_mfma_f32_16x16x32_bf16 v[110:113], v[160:163], v[192:195], v[110:113]
	v_mfma_f32_16x16x32_bf16 v[110:113], v[164:167], v[196:199], v[110:113]
	v_mfma_f32_16x16x32_bf16 v[94:97], v[160:163], v[200:203], v[94:97]
	v_mfma_f32_16x16x32_bf16 v[94:97], v[164:167], v[204:207], v[94:97]
	v_mfma_f32_16x16x32_bf16 v[78:81], v[160:163], v[210:213], v[78:81]
	v_mfma_f32_16x16x32_bf16 v[78:81], v[164:167], v[214:217], v[78:81]
	s_setprio 0
	s_setprio 1
	v_mfma_f32_16x16x32_bf16 v[114:117], v[168:171], v[184:187], v[114:117]
	v_mfma_f32_16x16x32_bf16 v[114:117], v[172:175], v[188:191], v[114:117]
	v_mfma_f32_16x16x32_bf16 v[98:101], v[168:171], v[192:195], v[98:101]
	v_mfma_f32_16x16x32_bf16 v[98:101], v[172:175], v[196:199], v[98:101]
	v_mfma_f32_16x16x32_bf16 v[82:85], v[168:171], v[200:203], v[82:85]
	v_mfma_f32_16x16x32_bf16 v[82:85], v[172:175], v[204:207], v[82:85]
	v_mfma_f32_16x16x32_bf16 v[70:73], v[168:171], v[210:213], v[70:73]
	v_mfma_f32_16x16x32_bf16 v[70:73], v[172:175], v[214:217], v[70:73]
	v_mfma_f32_16x16x32_bf16 v[106:109], v[176:179], v[184:187], v[106:109]
	v_mfma_f32_16x16x32_bf16 v[106:109], v[180:183], v[188:191], v[106:109]
	v_mfma_f32_16x16x32_bf16 v[90:93], v[176:179], v[192:195], v[90:93]
	v_mfma_f32_16x16x32_bf16 v[90:93], v[180:183], v[196:199], v[90:93]
	v_mfma_f32_16x16x32_bf16 v[74:77], v[176:179], v[200:203], v[74:77]
	v_mfma_f32_16x16x32_bf16 v[74:77], v[180:183], v[204:207], v[74:77]
	v_mfma_f32_16x16x32_bf16 v[66:69], v[176:179], v[210:213], v[66:69]
	v_mfma_f32_16x16x32_bf16 v[66:69], v[180:183], v[214:217], v[66:69]
	s_setprio 0
	s_barrier
; #define PG8_STAGE(bufoff, gbase, voff) do { _Pragma("unroll") for (int _i = 0; _i < 2; ++_i) \
;         __builtin_amdgcn_global_load_lds((const unsigned*)((const char*)(gbase) + (voff)[_i]), (PG8_LAS unsigned*)(lds + (bufoff) + ldsw + _i * 8192), 16, 0, 0); } while (0)
; #define PG8_LDA(dst, b, h) do { _Pragma("unroll") for (int m = 0; m < 4; ++m) _Pragma("unroll") for (int k = 0; k < 2; ++k) dst[m][k] = *(const PG8_LAS bf16x8*)(lds + PG8_SA(b, h) + aoff + m * 2048 + k * 1024); } while (0)
; #define PG8_MMA(ai, bj, At, Bt) do { __builtin_amdgcn_s_setprio(1); _Pragma("unroll") for (int m = 0; m < 4; ++m) _Pragma("unroll") for (int n = 0; n < 2; ++n) _Pragma("unroll") for (int k = 0; k < 2; ++k) \
;         acc[ai][bj][m][n] = __builtin_amdgcn_mfma_f32_16x16x32_bf16(Bt[n][k], At[m][k], acc[ai][bj][m][n], 0, 0, 0); __builtin_amdgcn_s_setprio(0); } while (0)
; #define PG8_WAIT_V(n) asm volatile("s_waitcnt vmcnt(" #n ")" ::: "memory")
; #define PG8_WAIT_L(n) asm volatile("s_waitcnt lgkmcnt(" #n ")" ::: "memory")
; #define PG8_BAR __builtin_amdgcn_s_barrier()
; #define PG8_SCHED __builtin_amdgcn_sched_barrier(0)
; template <class Epi, class Sched, bool ALIGN_EPI = false, bool SP2 = false>
; __device__ __forceinline__ void gemm_phase(PG8_LAS unsigned char* lds, const Gemm g, const Sched& S, const Epi& E) {
;     ...
;             PG8_LDA(At, 1, 1); PG8_STAGE(PG8_SB(1, 0), b3, voffB); PG8_STAGE(PG8_SB(1, 1), b3 + hstep, voffB); PG8_STAGE(PG8_SA(1, 0), a3, voffA);
;             PG8_WAIT_V(8); PG8_WAIT_L(0); PG8_BAR; PG8_MMA(1, 0, At, B0); PG8_MMA(1, 1, At, B1); PG8_BAR; PG8_SCHED;
	s_add_i32 s34, s62, s37
	v_lshl_add_u64 v[144:145], v[144:145], 0, s[6:7]
	s_mov_b32 m0, s34
	ds_read_b128 v[184:187], v151 offset:49152
	ds_read_b128 v[188:191], v151 offset:50176
	ds_read_b128 v[192:195], v151 offset:51200
	ds_read_b128 v[196:199], v151 offset:52224
	ds_read_b128 v[200:203], v151 offset:53248
	ds_read_b128 v[204:207], v151 offset:54272
	ds_read_b128 v[210:213], v151 offset:55296
	ds_read_b128 v[214:217], v151 offset:56320
	global_load_lds_dwordx4 v[144:145], off
	s_add_i32 m0, s34, 0x2000
	s_add_u32 s30, s30, 0x80080
	v_lshl_add_u64 v[144:145], v[218:219], 0, s[6:7]
	s_addc_u32 s31, s31, 0
	s_add_i32 s34, s63, s37
	global_load_lds_dwordx4 v[144:145], off
	v_lshl_add_u64 v[144:145], s[30:31], 0, v[134:135]
	s_mov_b32 m0, s34
	s_nop 0
	global_load_lds_dwordx4 v[144:145], off
	v_lshl_add_u64 v[144:145], s[30:31], 0, v[130:131]
	s_add_i32 m0, s34, 0x2000
	s_nop 0
	global_load_lds_dwordx4 v[144:145], off
	v_lshl_add_u64 v[144:145], v[220:221], 0, s[6:7]
	s_mov_b32 m0, s48
	s_nop 0
	global_load_lds_dwordx4 v[144:145], off
	v_lshl_add_u64 v[144:145], v[222:223], 0, s[6:7]
	s_mov_b32 m0, s49
	s_nop 0
	global_load_lds_dwordx4 v[144:145], off
	s_waitcnt vmcnt(8)
	s_waitcnt lgkmcnt(0)
	s_barrier
	s_setprio 1
	s_waitcnt lgkmcnt(0)
	v_mfma_f32_16x16x32_bf16 v[62:65], v[152:155], v[184:187], v[62:65]
	v_mfma_f32_16x16x32_bf16 v[62:65], v[156:159], v[188:191], v[62:65]
	v_mfma_f32_16x16x32_bf16 v[54:57], v[152:155], v[192:195], v[54:57]
	v_mfma_f32_16x16x32_bf16 v[54:57], v[156:159], v[196:199], v[54:57]
	v_mfma_f32_16x16x32_bf16 v[38:41], v[152:155], v[200:203], v[38:41]
	v_mfma_f32_16x16x32_bf16 v[38:41], v[156:159], v[204:207], v[38:41]
	v_mfma_f32_16x16x32_bf16 v[22:25], v[152:155], v[210:213], v[22:25]
	v_mfma_f32_16x16x32_bf16 v[22:25], v[156:159], v[214:217], v[22:25]
	v_mfma_f32_16x16x32_bf16 v[58:61], v[160:163], v[184:187], v[58:61]
	v_mfma_f32_16x16x32_bf16 v[58:61], v[164:167], v[188:191], v[58:61]
	v_mfma_f32_16x16x32_bf16 v[46:49], v[160:163], v[192:195], v[46:49]
	v_mfma_f32_16x16x32_bf16 v[46:49], v[164:167], v[196:199], v[46:49]
	v_mfma_f32_16x16x32_bf16 v[30:33], v[160:163], v[200:203], v[30:33]
	v_mfma_f32_16x16x32_bf16 v[30:33], v[164:167], v[204:207], v[30:33]
	v_mfma_f32_16x16x32_bf16 v[14:17], v[160:163], v[210:213], v[14:17]
	v_mfma_f32_16x16x32_bf16 v[14:17], v[164:167], v[214:217], v[14:17]
	s_setprio 0
	s_setprio 1
	v_mfma_f32_16x16x32_bf16 v[50:53], v[168:171], v[184:187], v[50:53]
	v_mfma_f32_16x16x32_bf16 v[50:53], v[172:175], v[188:191], v[50:53]
	v_mfma_f32_16x16x32_bf16 v[34:37], v[168:171], v[192:195], v[34:37]
	v_mfma_f32_16x16x32_bf16 v[34:37], v[172:175], v[196:199], v[34:37]
	v_mfma_f32_16x16x32_bf16 v[18:21], v[168:171], v[200:203], v[18:21]
	v_mfma_f32_16x16x32_bf16 v[18:21], v[172:175], v[204:207], v[18:21]
	v_mfma_f32_16x16x32_bf16 v[6:9], v[168:171], v[210:213], v[6:9]
	v_mfma_f32_16x16x32_bf16 v[6:9], v[172:175], v[214:217], v[6:9]
	v_mfma_f32_16x16x32_bf16 v[42:45], v[176:179], v[184:187], v[42:45]
	v_mfma_f32_16x16x32_bf16 v[42:45], v[180:183], v[188:191], v[42:45]
	v_mfma_f32_16x16x32_bf16 v[26:29], v[176:179], v[192:195], v[26:29]
	v_mfma_f32_16x16x32_bf16 v[26:29], v[180:183], v[196:199], v[26:29]
	v_mfma_f32_16x16x32_bf16 v[10:13], v[176:179], v[200:203], v[10:13]
	v_mfma_f32_16x16x32_bf16 v[10:13], v[180:183], v[204:207], v[10:13]
	v_mfma_f32_16x16x32_bf16 v[2:5], v[176:179], v[210:213], v[2:5]
	v_mfma_f32_16x16x32_bf16 v[2:5], v[180:183], v[214:217], v[2:5]
	s_setprio 0
	s_barrier
	s_add_i32 s61, s61, 2
	s_add_u32 s28, s28, 0x100
	s_addc_u32 s29, s29, 0
	s_add_u32 s59, s59, 0x100
	s_addc_u32 s60, s60, 0
	s_cmp_gt_u32 s61, 29
	s_cbranch_scc0 .LBB11_228
	s_and_b64 vcc, exec, s[8:9]
	s_cbranch_vccz .LBB11_231
	s_barrier

; #define PG8_STAGE(bufoff, gbase, voff) do { _Pragma("unroll") for (int _i = 0; _i < 2; ++_i) \
;         __builtin_amdgcn_global_load_lds((const unsigned*)((const char*)(gbase) + (voff)[_i]), (PG8_LAS unsigned*)(lds + (bufoff) + ldsw + _i * 8192), 16, 0, 0); } while (0)
; #define PG8_LDA(dst, b, h) do { _Pragma("unroll") for (int m = 0; m < 4; ++m) _Pragma("unroll") for (int k = 0; k < 2; ++k) dst[m][k] = *(const PG8_LAS bf16x8*)(lds + PG8_SA(b, h) + aoff + m * 2048 + k * 1024); } while (0)
; #define PG8_LDB(dst, b, h) do { _Pragma("unroll") for (int n = 0; n < 2; ++n) _Pragma("unroll") for (int k = 0; k < 2; ++k) dst[n][k] = *(const PG8_LAS bf16x8*)(lds + PG8_SB(b, h) + boff + n * 2048 + k * 1024); } while (0)
; #define PG8_MMA(ai, bj, At, Bt) do { __builtin_amdgcn_s_setprio(1); _Pragma("unroll") for (int m = 0; m < 4; ++m) _Pragma("unroll") for (int n = 0; n < 2; ++n) _Pragma("unroll") for (int k = 0; k < 2; ++k) \
;         acc[ai][bj][m][n] = __builtin_amdgcn_mfma_f32_16x16x32_bf16(Bt[n][k], At[m][k], acc[ai][bj][m][n], 0, 0, 0); __builtin_amdgcn_s_setprio(0); } while (0)
; #define PG8_WAIT_V(n) asm volatile("s_waitcnt vmcnt(" #n ")" ::: "memory")
; #define PG8_WAIT_L(n) asm volatile("s_waitcnt lgkmcnt(" #n ")" ::: "memory")
; #define PG8_BAR __builtin_amdgcn_s_barrier()
; #define PG8_SCHED __builtin_amdgcn_sched_barrier(0)
; template <class Epi, class Sched, bool ALIGN_EPI = false, bool SP2 = false>
; __device__ __forceinline__ void gemm_phase(PG8_LAS unsigned char* lds, const Gemm g, const Sched& S, const Epi& E) {
;     ...
;             const char* a2 = last ? nA : cA + (size_t)(t + 2) * kstep; const char* b2 = last ? nB : cB + (size_t)(t + 2) * kstep;
;             const char* a3 = a2 + kstep; const char* b3 = b2 + kstep;
;             if (last && has_next) S.a_ready(nxt);
;             if constexpr (SP2) {
;             PG8_LDB(B0, 0, 0); PG8_LDB(B1, 0, 1); PG8_SCHED; PG8_LDA(At, 0, 0); PG8_STAGE(PG8_SA(1, 1), a1 + hstep, voffA);
;             PG8_WAIT_V(8); PG8_WAIT_L(0); PG8_BAR; PG8_MMA(0, 0, At, B0); PG8_MMA(0, 1, At, B1); PG8_BAR; PG8_SCHED;
;             PG8_LDA(At, 0, 1); PG8_STAGE(PG8_SB(0, 0), b2, voffB); PG8_STAGE(PG8_SB(0, 1), b2 + hstep, voffB); PG8_STAGE(PG8_SA(0, 0), a2, voffA);
;             PG8_WAIT_V(8); PG8_WAIT_L(0); PG8_BAR; PG8_MMA(1, 0, At, B0); PG8_MMA(1, 1, At, B1); PG8_BAR; PG8_SCHED;
.LBB11_456:
	s_add_u32 s18, s16, 0xfff80080
	s_addc_u32 s19, s17, -1
	s_add_i32 s49, 0, 0x10000
	s_cmp_eq_u32 s48, 28
	s_cselect_b32 s21, s11, s19
	s_cselect_b32 s20, s44, s18
	v_add_u32_e32 v144, s49, v147
	s_cselect_b32 s19, s9, s47
	s_cselect_b32 s18, s45, s46
	s_add_i32 s52, 0, 0x14000
	ds_read_b128 v[150:153], v144
	ds_read_b128 v[154:157], v144 offset:1024
	ds_read_b128 v[158:161], v144 offset:2048
	ds_read_b128 v[162:165], v144 offset:3072
	v_add_u32_e32 v144, s52, v147
	ds_read_b128 v[166:169], v144
	ds_read_b128 v[170:173], v144 offset:1024
	ds_read_b128 v[174:177], v144 offset:2048
	ds_read_b128 v[178:181], v144 offset:3072
	v_lshl_add_u64 v[144:145], s[16:17], 0, v[140:141]
	s_add_i32 m0, s29, 0xc000
	ds_read_b128 v[198:201], v149
	ds_read_b128 v[202:205], v149 offset:1024
	ds_read_b128 v[220:223], v149 offset:2048
	ds_read_b128 v[224:227], v149 offset:3072
	ds_read_b128 v[228:231], v149 offset:4096
	ds_read_b128 v[232:235], v149 offset:5120
	ds_read_b128 v[236:239], v149 offset:6144
	ds_read_b128 v[240:243], v149 offset:7168
	global_load_lds_dwordx4 v[144:145], off
	v_lshl_add_u64 v[144:145], s[16:17], 0, v[142:143]
	s_add_i32 m0, s29, 0xe000
	s_nop 0
	global_load_lds_dwordx4 v[144:145], off
	s_waitcnt vmcnt(8)
	s_waitcnt lgkmcnt(0)
	s_barrier
	s_setprio 1
	s_waitcnt lgkmcnt(0)
	v_mfma_f32_16x16x32_bf16 v[124:127], v[150:153], v[198:201], v[124:127]
	v_mfma_f32_16x16x32_bf16 v[124:127], v[154:157], v[202:205], v[124:127]
	v_mfma_f32_16x16x32_bf16 v[108:111], v[150:153], v[220:223], v[108:111]
	v_mfma_f32_16x16x32_bf16 v[108:111], v[154:157], v[224:227], v[108:111]
	v_mfma_f32_16x16x32_bf16 v[92:95], v[150:153], v[228:231], v[92:95]
	v_mfma_f32_16x16x32_bf16 v[92:95], v[154:157], v[232:235], v[92:95]
	v_mfma_f32_16x16x32_bf16 v[76:79], v[150:153], v[236:239], v[76:79]
	v_mfma_f32_16x16x32_bf16 v[76:79], v[154:157], v[240:243], v[76:79]
	v_mfma_f32_16x16x32_bf16 v[116:119], v[158:161], v[198:201], v[116:119]
	v_mfma_f32_16x16x32_bf16 v[116:119], v[162:165], v[202:205], v[116:119]
	v_mfma_f32_16x16x32_bf16 v[100:103], v[158:161], v[220:223], v[100:103]
	v_mfma_f32_16x16x32_bf16 v[100:103], v[162:165], v[224:227], v[100:103]
	v_mfma_f32_16x16x32_bf16 v[84:87], v[158:161], v[228:231], v[84:87]
	v_mfma_f32_16x16x32_bf16 v[84:87], v[162:165], v[232:235], v[84:87]
	v_mfma_f32_16x16x32_bf16 v[68:71], v[158:161], v[236:239], v[68:71]
	v_mfma_f32_16x16x32_bf16 v[68:71], v[162:165], v[240:243], v[68:71]
	s_setprio 0
	s_setprio 1
	v_mfma_f32_16x16x32_bf16 v[128:131], v[166:169], v[198:201], v[128:131]
	v_mfma_f32_16x16x32_bf16 v[128:131], v[170:173], v[202:205], v[128:131]
	v_mfma_f32_16x16x32_bf16 v[112:115], v[166:169], v[220:223], v[112:115]
	v_mfma_f32_16x16x32_bf16 v[112:115], v[170:173], v[224:227], v[112:115]
	v_mfma_f32_16x16x32_bf16 v[96:99], v[166:169], v[228:231], v[96:99]
	v_mfma_f32_16x16x32_bf16 v[96:99], v[170:173], v[232:235], v[96:99]
	v_mfma_f32_16x16x32_bf16 v[80:83], v[166:169], v[236:239], v[80:83]
	v_mfma_f32_16x16x32_bf16 v[80:83], v[170:173], v[240:243], v[80:83]
	v_mfma_f32_16x16x32_bf16 v[120:123], v[174:177], v[198:201], v[120:123]
	v_mfma_f32_16x16x32_bf16 v[120:123], v[178:181], v[202:205], v[120:123]
	v_mfma_f32_16x16x32_bf16 v[104:107], v[174:177], v[220:223], v[104:107]
	v_mfma_f32_16x16x32_bf16 v[104:107], v[178:181], v[224:227], v[104:107]
	v_mfma_f32_16x16x32_bf16 v[88:91], v[174:177], v[228:231], v[88:91]
	v_mfma_f32_16x16x32_bf16 v[88:91], v[178:181], v[232:235], v[88:91]
	v_mfma_f32_16x16x32_bf16 v[72:75], v[174:177], v[236:239], v[72:75]
	v_mfma_f32_16x16x32_bf16 v[72:75], v[178:181], v[240:243], v[72:75]
	s_setprio 0
	s_barrier
	s_add_i32 s49, s49, s27
	v_lshl_add_u64 v[144:145], s[18:19], 0, v[2:3]
	s_mov_b32 m0, s49
	ds_read_b128 v[198:201], v149 offset:16384
	ds_read_b128 v[202:205], v149 offset:17408
	ds_read_b128 v[220:223], v149 offset:18432
	ds_read_b128 v[224:227], v149 offset:19456
	ds_read_b128 v[228:231], v149 offset:20480
	ds_read_b128 v[232:235], v149 offset:21504
	ds_read_b128 v[236:239], v149 offset:22528
	ds_read_b128 v[240:243], v149 offset:23552
	global_load_lds_dwordx4 v[144:145], off
	s_add_i32 m0, s49, 0x2000
	s_add_u32 s50, s18, 0x80000
	v_lshl_add_u64 v[206:207], s[18:19], 0, v[132:133]
	s_addc_u32 s51, s19, 0
	s_add_i32 s49, s52, s27
	global_load_lds_dwordx4 v[206:207], off
	v_lshl_add_u64 v[244:245], s[50:51], 0, v[2:3]
	s_mov_b32 m0, s49
	v_lshl_add_u64 v[246:247], s[20:21], 0, v[134:135]
	global_load_lds_dwordx4 v[244:245], off
	v_lshl_add_u64 v[244:245], s[50:51], 0, v[132:133]
	s_add_i32 m0, s49, 0x2000
	s_nop 0
	global_load_lds_dwordx4 v[244:245], off
	v_lshl_add_u64 v[244:245], s[20:21], 0, v[136:137]
	s_mov_b32 m0, s29
	s_nop 0
	global_load_lds_dwordx4 v[244:245], off
	s_mov_b32 m0, s30
	s_nop 0
	global_load_lds_dwordx4 v[246:247], off
	s_waitcnt vmcnt(8)
	s_waitcnt lgkmcnt(0)
	s_barrier
; #define PG8_STAGE(bufoff, gbase, voff) do { _Pragma("unroll") for (int _i = 0; _i < 2; ++_i) \
;         __builtin_amdgcn_global_load_lds((const unsigned*)((const char*)(gbase) + (voff)[_i]), (PG8_LAS unsigned*)(lds + (bufoff) + ldsw + _i * 8192), 16, 0, 0); } while (0)
; #define PG8_LDA(dst, b, h) do { _Pragma("unroll") for (int m = 0; m < 4; ++m) _Pragma("unroll") for (int k = 0; k < 2; ++k) dst[m][k] = *(const PG8_LAS bf16x8*)(lds + PG8_SA(b, h) + aoff + m * 2048 + k * 1024); } while (0)
; #define PG8_LDB(dst, b, h) do { _Pragma("unroll") for (int n = 0; n < 2; ++n) _Pragma("unroll") for (int k = 0; k < 2; ++k) dst[n][k] = *(const PG8_LAS bf16x8*)(lds + PG8_SB(b, h) + boff + n * 2048 + k * 1024); } while (0)
; #define PG8_MMA(ai, bj, At, Bt) do { __builtin_amdgcn_s_setprio(1); _Pragma("unroll") for (int m = 0; m < 4; ++m) _Pragma("unroll") for (int n = 0; n < 2; ++n) _Pragma("unroll") for (int k = 0; k < 2; ++k) \
;         acc[ai][bj][m][n] = __builtin_amdgcn_mfma_f32_16x16x32_bf16(Bt[n][k], At[m][k], acc[ai][bj][m][n], 0, 0, 0); __builtin_amdgcn_s_setprio(0); } while (0)
; #define PG8_WAIT_V(n) asm volatile("s_waitcnt vmcnt(" #n ")" ::: "memory")
; #define PG8_WAIT_L(n) asm volatile("s_waitcnt lgkmcnt(" #n ")" ::: "memory")
; #define PG8_BAR __builtin_amdgcn_s_barrier()
; #define PG8_SCHED __builtin_amdgcn_sched_barrier(0)
; template <class Epi, class Sched, bool ALIGN_EPI = false, bool SP2 = false>
; __device__ __forceinline__ void gemm_phase(PG8_LAS unsigned char* lds, const Gemm g, const Sched& S, const Epi& E) {
;     ...
;             PG8_WAIT_V(8); PG8_WAIT_L(0); PG8_BAR; PG8_MMA(1, 0, At, B0); PG8_MMA(1, 1, At, B1); PG8_BAR; PG8_SCHED;
;             PG8_LDB(B0, 1, 0); PG8_LDB(B1, 1, 1); PG8_SCHED; PG8_LDA(At, 1, 0); PG8_STAGE(PG8_SA(0, 1), a2 + hstep, voffA);
;             PG8_WAIT_V(8); PG8_WAIT_L(0); PG8_BAR; PG8_MMA(0, 0, At, B0); PG8_MMA(0, 1, At, B1); PG8_BAR; PG8_SCHED;
	s_setprio 1
	s_waitcnt lgkmcnt(0)
	v_mfma_f32_16x16x32_bf16 v[60:63], v[150:153], v[198:201], v[60:63]
	v_mfma_f32_16x16x32_bf16 v[60:63], v[154:157], v[202:205], v[60:63]
	v_mfma_f32_16x16x32_bf16 v[44:47], v[150:153], v[220:223], v[44:47]
	v_mfma_f32_16x16x32_bf16 v[44:47], v[154:157], v[224:227], v[44:47]
	v_mfma_f32_16x16x32_bf16 v[28:31], v[150:153], v[228:231], v[28:31]
	v_mfma_f32_16x16x32_bf16 v[28:31], v[154:157], v[232:235], v[28:31]
	v_mfma_f32_16x16x32_bf16 v[12:15], v[150:153], v[236:239], v[12:15]
	v_mfma_f32_16x16x32_bf16 v[12:15], v[154:157], v[240:243], v[12:15]
	v_mfma_f32_16x16x32_bf16 v[52:55], v[158:161], v[198:201], v[52:55]
	v_mfma_f32_16x16x32_bf16 v[52:55], v[162:165], v[202:205], v[52:55]
	v_mfma_f32_16x16x32_bf16 v[36:39], v[158:161], v[220:223], v[36:39]
	v_mfma_f32_16x16x32_bf16 v[36:39], v[162:165], v[224:227], v[36:39]
	v_mfma_f32_16x16x32_bf16 v[20:23], v[158:161], v[228:231], v[20:23]
	v_mfma_f32_16x16x32_bf16 v[20:23], v[162:165], v[232:235], v[20:23]
	v_mfma_f32_16x16x32_bf16 v[4:7], v[158:161], v[236:239], v[4:7]
	v_mfma_f32_16x16x32_bf16 v[4:7], v[162:165], v[240:243], v[4:7]
	s_setprio 0
	s_setprio 1
	v_mfma_f32_16x16x32_bf16 v[64:67], v[166:169], v[198:201], v[64:67]
	v_mfma_f32_16x16x32_bf16 v[64:67], v[170:173], v[202:205], v[64:67]
	v_mfma_f32_16x16x32_bf16 v[48:51], v[166:169], v[220:223], v[48:51]
	v_mfma_f32_16x16x32_bf16 v[48:51], v[170:173], v[224:227], v[48:51]
	v_mfma_f32_16x16x32_bf16 v[32:35], v[166:169], v[228:231], v[32:35]
	v_mfma_f32_16x16x32_bf16 v[32:35], v[170:173], v[232:235], v[32:35]
	v_mfma_f32_16x16x32_bf16 v[16:19], v[166:169], v[236:239], v[16:19]
	v_mfma_f32_16x16x32_bf16 v[16:19], v[170:173], v[240:243], v[16:19]
	v_mfma_f32_16x16x32_bf16 v[56:59], v[174:177], v[198:201], v[56:59]
	v_mfma_f32_16x16x32_bf16 v[56:59], v[178:181], v[202:205], v[56:59]
	v_mfma_f32_16x16x32_bf16 v[40:43], v[174:177], v[220:223], v[40:43]
	v_mfma_f32_16x16x32_bf16 v[40:43], v[178:181], v[224:227], v[40:43]
	v_mfma_f32_16x16x32_bf16 v[24:27], v[174:177], v[228:231], v[24:27]
	v_mfma_f32_16x16x32_bf16 v[24:27], v[178:181], v[232:235], v[24:27]
	v_mfma_f32_16x16x32_bf16 v[8:11], v[174:177], v[236:239], v[8:11]
	v_mfma_f32_16x16x32_bf16 v[8:11], v[178:181], v[240:243], v[8:11]
	s_setprio 0
	s_barrier
	s_add_i32 s49, 0, 0x18000
	s_add_i32 s50, 0, 0x1c000
	v_add_u32_e32 v162, s49, v147
	v_add_u32_e32 v178, s50, v147
	ds_read_b128 v[150:153], v162
	ds_read_b128 v[154:157], v162 offset:1024
	ds_read_b128 v[158:161], v162 offset:2048
	ds_read_b128 v[162:165], v162 offset:3072
	ds_read_b128 v[166:169], v178
	ds_read_b128 v[170:173], v178 offset:1024
	ds_read_b128 v[174:177], v178 offset:2048
	ds_read_b128 v[178:181], v178 offset:3072
	s_add_u32 s20, s20, 0x80000
	s_addc_u32 s21, s21, 0
	s_mov_b32 m0, s33
	v_lshl_add_u64 v[196:197], s[20:21], 0, v[136:137]
	ds_read_b128 v[198:201], v149 offset:32768
	ds_read_b128 v[202:205], v149 offset:33792
	ds_read_b128 v[220:223], v149 offset:34816
	ds_read_b128 v[224:227], v149 offset:35840
	ds_read_b128 v[228:231], v149 offset:36864
	ds_read_b128 v[232:235], v149 offset:37888
	ds_read_b128 v[236:239], v149 offset:38912
	ds_read_b128 v[240:243], v149 offset:39936
	global_load_lds_dwordx4 v[196:197], off
	v_lshl_add_u64 v[196:197], s[20:21], 0, v[134:135]
	s_mov_b32 m0, s38
	s_nop 0
	global_load_lds_dwordx4 v[196:197], off
	s_waitcnt vmcnt(8)
	s_waitcnt lgkmcnt(0)
	s_barrier
	s_setprio 1
	s_waitcnt lgkmcnt(0)
	v_mfma_f32_16x16x32_bf16 v[124:127], v[150:153], v[198:201], v[124:127]
	v_mfma_f32_16x16x32_bf16 v[124:127], v[154:157], v[202:205], v[124:127]
	v_mfma_f32_16x16x32_bf16 v[108:111], v[150:153], v[220:223], v[108:111]
	v_mfma_f32_16x16x32_bf16 v[108:111], v[154:157], v[224:227], v[108:111]
	v_mfma_f32_16x16x32_bf16 v[92:95], v[150:153], v[228:231], v[92:95]
	v_mfma_f32_16x16x32_bf16 v[92:95], v[154:157], v[232:235], v[92:95]
	v_mfma_f32_16x16x32_bf16 v[76:79], v[150:153], v[236:239], v[76:79]
	v_mfma_f32_16x16x32_bf16 v[76:79], v[154:157], v[240:243], v[76:79]
	v_mfma_f32_16x16x32_bf16 v[116:119], v[158:161], v[198:201], v[116:119]
	v_mfma_f32_16x16x32_bf16 v[116:119], v[162:165], v[202:205], v[116:119]
	v_mfma_f32_16x16x32_bf16 v[100:103], v[158:161], v[220:223], v[100:103]
	v_mfma_f32_16x16x32_bf16 v[100:103], v[162:165], v[224:227], v[100:103]
	v_mfma_f32_16x16x32_bf16 v[84:87], v[158:161], v[228:231], v[84:87]
	v_mfma_f32_16x16x32_bf16 v[84:87], v[162:165], v[232:235], v[84:87]
	v_mfma_f32_16x16x32_bf16 v[68:71], v[158:161], v[236:239], v[68:71]
	v_mfma_f32_16x16x32_bf16 v[68:71], v[162:165], v[240:243], v[68:71]
	s_setprio 0
	s_setprio 1
	v_mfma_f32_16x16x32_bf16 v[128:131], v[166:169], v[198:201], v[128:131]
	v_mfma_f32_16x16x32_bf16 v[128:131], v[170:173], v[202:205], v[128:131]
	v_mfma_f32_16x16x32_bf16 v[112:115], v[166:169], v[220:223], v[112:115]
	v_mfma_f32_16x16x32_bf16 v[112:115], v[170:173], v[224:227], v[112:115]
	v_mfma_f32_16x16x32_bf16 v[96:99], v[166:169], v[228:231], v[96:99]
	v_mfma_f32_16x16x32_bf16 v[96:99], v[170:173], v[232:235], v[96:99]
	v_mfma_f32_16x16x32_bf16 v[80:83], v[166:169], v[236:239], v[80:83]
	v_mfma_f32_16x16x32_bf16 v[80:83], v[170:173], v[240:243], v[80:83]
	v_mfma_f32_16x16x32_bf16 v[120:123], v[174:177], v[198:201], v[120:123]
	v_mfma_f32_16x16x32_bf16 v[120:123], v[178:181], v[202:205], v[120:123]
	v_mfma_f32_16x16x32_bf16 v[104:107], v[174:177], v[220:223], v[104:107]
	v_mfma_f32_16x16x32_bf16 v[104:107], v[178:181], v[224:227], v[104:107]
	v_mfma_f32_16x16x32_bf16 v[88:91], v[174:177], v[228:231], v[88:91]
	v_mfma_f32_16x16x32_bf16 v[88:91], v[178:181], v[232:235], v[88:91]
	v_mfma_f32_16x16x32_bf16 v[72:75], v[174:177], v[236:239], v[72:75]
	v_mfma_f32_16x16x32_bf16 v[72:75], v[178:181], v[240:243], v[72:75]
	s_setprio 0
	s_barrier
; #define PG8_STAGE(bufoff, gbase, voff) do { _Pragma("unroll") for (int _i = 0; _i < 2; ++_i) \
;         __builtin_amdgcn_global_load_lds((const unsigned*)((const char*)(gbase) + (voff)[_i]), (PG8_LAS unsigned*)(lds + (bufoff) + ldsw + _i * 8192), 16, 0, 0); } while (0)
; #define PG8_LDA(dst, b, h) do { _Pragma("unroll") for (int m = 0; m < 4; ++m) _Pragma("unroll") for (int k = 0; k < 2; ++k) dst[m][k] = *(const PG8_LAS bf16x8*)(lds + PG8_SA(b, h) + aoff + m * 2048 + k * 1024); } while (0)
; #define PG8_MMA(ai, bj, At, Bt) do { __builtin_amdgcn_s_setprio(1); _Pragma("unroll") for (int m = 0; m < 4; ++m) _Pragma("unroll") for (int n = 0; n < 2; ++n) _Pragma("unroll") for (int k = 0; k < 2; ++k) \
;         acc[ai][bj][m][n] = __builtin_amdgcn_mfma_f32_16x16x32_bf16(Bt[n][k], At[m][k], acc[ai][bj][m][n], 0, 0, 0); __builtin_amdgcn_s_setprio(0); } while (0)
; #define PG8_WAIT_V(n) asm volatile("s_waitcnt vmcnt(" #n ")" ::: "memory")
; #define PG8_WAIT_L(n) asm volatile("s_waitcnt lgkmcnt(" #n ")" ::: "memory")
; #define PG8_BAR __builtin_amdgcn_s_barrier()
; #define PG8_SCHED __builtin_amdgcn_sched_barrier(0)
; template <class Epi, class Sched, bool ALIGN_EPI = false, bool SP2 = false>
; __device__ __forceinline__ void gemm_phase(PG8_LAS unsigned char* lds, const Gemm g, const Sched& S, const Epi& E) {
;     ...
;             PG8_LDA(At, 1, 1); PG8_STAGE(PG8_SB(1, 0), b3, voffB); PG8_STAGE(PG8_SB(1, 1), b3 + hstep, voffB); PG8_STAGE(PG8_SA(1, 0), a3, voffA);
;             PG8_WAIT_V(8); PG8_WAIT_L(0); PG8_BAR; PG8_MMA(1, 0, At, B0); PG8_MMA(1, 1, At, B1); PG8_BAR; PG8_SCHED;
	s_add_i32 s20, s49, s27
	v_lshl_add_u64 v[144:145], v[144:145], 0, s[34:35]
	s_mov_b32 m0, s20
	ds_read_b128 v[198:201], v149 offset:49152
	ds_read_b128 v[202:205], v149 offset:50176
	ds_read_b128 v[220:223], v149 offset:51200
	ds_read_b128 v[224:227], v149 offset:52224
	ds_read_b128 v[228:231], v149 offset:53248
	ds_read_b128 v[232:235], v149 offset:54272
	ds_read_b128 v[236:239], v149 offset:55296
	ds_read_b128 v[240:243], v149 offset:56320
	global_load_lds_dwordx4 v[144:145], off
	s_add_i32 m0, s20, 0x2000
	s_add_u32 s18, s18, 0x80080
	v_lshl_add_u64 v[144:145], v[206:207], 0, s[34:35]
	s_addc_u32 s19, s19, 0
	s_add_i32 s20, s50, s27
	global_load_lds_dwordx4 v[144:145], off
	v_lshl_add_u64 v[144:145], s[18:19], 0, v[2:3]
	s_mov_b32 m0, s20
	s_nop 0
	global_load_lds_dwordx4 v[144:145], off
	v_lshl_add_u64 v[144:145], s[18:19], 0, v[132:133]
	s_add_i32 m0, s20, 0x2000
	s_nop 0
	global_load_lds_dwordx4 v[144:145], off
	v_lshl_add_u64 v[144:145], v[244:245], 0, s[34:35]
	s_mov_b32 m0, s39
	s_nop 0
	global_load_lds_dwordx4 v[144:145], off
	v_lshl_add_u64 v[144:145], v[246:247], 0, s[34:35]
	s_mov_b32 m0, s40
	s_nop 0
	global_load_lds_dwordx4 v[144:145], off
	s_waitcnt vmcnt(8)
	s_waitcnt lgkmcnt(0)
	s_barrier
	s_setprio 1
	s_waitcnt lgkmcnt(0)
	v_mfma_f32_16x16x32_bf16 v[60:63], v[150:153], v[198:201], v[60:63]
	v_mfma_f32_16x16x32_bf16 v[60:63], v[154:157], v[202:205], v[60:63]
	v_mfma_f32_16x16x32_bf16 v[44:47], v[150:153], v[220:223], v[44:47]
	v_mfma_f32_16x16x32_bf16 v[44:47], v[154:157], v[224:227], v[44:47]
	v_mfma_f32_16x16x32_bf16 v[28:31], v[150:153], v[228:231], v[28:31]
	v_mfma_f32_16x16x32_bf16 v[28:31], v[154:157], v[232:235], v[28:31]
	v_mfma_f32_16x16x32_bf16 v[12:15], v[150:153], v[236:239], v[12:15]
	v_mfma_f32_16x16x32_bf16 v[12:15], v[154:157], v[240:243], v[12:15]
	v_mfma_f32_16x16x32_bf16 v[52:55], v[158:161], v[198:201], v[52:55]
	v_mfma_f32_16x16x32_bf16 v[52:55], v[162:165], v[202:205], v[52:55]
	v_mfma_f32_16x16x32_bf16 v[36:39], v[158:161], v[220:223], v[36:39]
	v_mfma_f32_16x16x32_bf16 v[36:39], v[162:165], v[224:227], v[36:39]
	v_mfma_f32_16x16x32_bf16 v[20:23], v[158:161], v[228:231], v[20:23]
	v_mfma_f32_16x16x32_bf16 v[20:23], v[162:165], v[232:235], v[20:23]
	v_mfma_f32_16x16x32_bf16 v[4:7], v[158:161], v[236:239], v[4:7]
	v_mfma_f32_16x16x32_bf16 v[4:7], v[162:165], v[240:243], v[4:7]
	s_setprio 0
	s_setprio 1
	v_mfma_f32_16x16x32_bf16 v[64:67], v[166:169], v[198:201], v[64:67]
	v_mfma_f32_16x16x32_bf16 v[64:67], v[170:173], v[202:205], v[64:67]
	v_mfma_f32_16x16x32_bf16 v[48:51], v[166:169], v[220:223], v[48:51]
	v_mfma_f32_16x16x32_bf16 v[48:51], v[170:173], v[224:227], v[48:51]
	v_mfma_f32_16x16x32_bf16 v[32:35], v[166:169], v[228:231], v[32:35]
	v_mfma_f32_16x16x32_bf16 v[32:35], v[170:173], v[232:235], v[32:35]
	v_mfma_f32_16x16x32_bf16 v[16:19], v[166:169], v[236:239], v[16:19]
	v_mfma_f32_16x16x32_bf16 v[16:19], v[170:173], v[240:243], v[16:19]
	v_mfma_f32_16x16x32_bf16 v[56:59], v[174:177], v[198:201], v[56:59]
	v_mfma_f32_16x16x32_bf16 v[56:59], v[178:181], v[202:205], v[56:59]
	v_mfma_f32_16x16x32_bf16 v[40:43], v[174:177], v[220:223], v[40:43]
	v_mfma_f32_16x16x32_bf16 v[40:43], v[178:181], v[224:227], v[40:43]
	v_mfma_f32_16x16x32_bf16 v[24:27], v[174:177], v[228:231], v[24:27]
	v_mfma_f32_16x16x32_bf16 v[24:27], v[178:181], v[232:235], v[24:27]
	v_mfma_f32_16x16x32_bf16 v[8:11], v[174:177], v[236:239], v[8:11]
	v_mfma_f32_16x16x32_bf16 v[8:11], v[178:181], v[240:243], v[8:11]
	s_setprio 0
	s_barrier
	s_add_i32 s48, s48, 2
	s_add_u32 s16, s16, 0x100
	s_addc_u32 s17, s17, 0
	s_add_u32 s46, s46, 0x100
	s_addc_u32 s47, s47, 0
	s_cmp_gt_u32 s48, 29
	s_cbranch_scc0 .LBB11_456
	s_and_b64 vcc, exec, s[6:7]
	s_cbranch_vccz .LBB11_459
	s_barrier

; #define PG8_STAGE(bufoff, gbase, voff) do { _Pragma("unroll") for (int _i = 0; _i < 2; ++_i) \
;         __builtin_amdgcn_global_load_lds((const unsigned*)((const char*)(gbase) + (voff)[_i]), (PG8_LAS unsigned*)(lds + (bufoff) + ldsw + _i * 8192), 16, 0, 0); } while (0)
; #define PG8_LDA(dst, b, h) do { _Pragma("unroll") for (int m = 0; m < 4; ++m) _Pragma("unroll") for (int k = 0; k < 2; ++k) dst[m][k] = *(const PG8_LAS bf16x8*)(lds + PG8_SA(b, h) + aoff + m * 2048 + k * 1024); } while (0)
; #define PG8_LDB(dst, b, h) do { _Pragma("unroll") for (int n = 0; n < 2; ++n) _Pragma("unroll") for (int k = 0; k < 2; ++k) dst[n][k] = *(const PG8_LAS bf16x8*)(lds + PG8_SB(b, h) + boff + n * 2048 + k * 1024); } while (0)
; #define PG8_MMA(ai, bj, At, Bt) do { __builtin_amdgcn_s_setprio(1); _Pragma("unroll") for (int m = 0; m < 4; ++m) _Pragma("unroll") for (int n = 0; n < 2; ++n) _Pragma("unroll") for (int k = 0; k < 2; ++k) \
;         acc[ai][bj][m][n] = __builtin_amdgcn_mfma_f32_16x16x32_bf16(Bt[n][k], At[m][k], acc[ai][bj][m][n], 0, 0, 0); __builtin_amdgcn_s_setprio(0); } while (0)
; #define PG8_WAIT_V(n) asm volatile("s_waitcnt vmcnt(" #n ")" ::: "memory")
; #define PG8_WAIT_L(n) asm volatile("s_waitcnt lgkmcnt(" #n ")" ::: "memory")
; #define PG8_BAR __builtin_amdgcn_s_barrier()
; #define PG8_SCHED __builtin_amdgcn_sched_barrier(0)
; template <class Epi, class Sched, bool ALIGN_EPI = false, bool SP2 = false>
; __device__ __forceinline__ void gemm_phase(PG8_LAS unsigned char* lds, const Gemm g, const Sched& S, const Epi& E) {
;     ...
;             const char* a2 = last ? nA : cA + (size_t)(t + 2) * kstep; const char* b2 = last ? nB : cB + (size_t)(t + 2) * kstep;
;             const char* a3 = a2 + kstep; const char* b3 = b2 + kstep;
;             if (last && has_next) S.a_ready(nxt);
;             if constexpr (SP2) {
;             PG8_LDB(B0, 0, 0); PG8_LDB(B1, 0, 1); PG8_SCHED; PG8_LDA(At, 0, 0); PG8_STAGE(PG8_SA(1, 1), a1 + hstep, voffA);
;             PG8_WAIT_V(8); PG8_WAIT_L(0); PG8_BAR; PG8_MMA(0, 0, At, B0); PG8_MMA(0, 1, At, B1); PG8_BAR; PG8_SCHED;
;             PG8_LDA(At, 0, 1); PG8_STAGE(PG8_SB(0, 0), b2, voffB); PG8_STAGE(PG8_SB(0, 1), b2 + hstep, voffB); PG8_STAGE(PG8_SA(0, 0), a2, voffA);
;             PG8_WAIT_V(8); PG8_WAIT_L(0); PG8_BAR; PG8_MMA(1, 0, At, B0); PG8_MMA(1, 1, At, B1); PG8_BAR; PG8_SCHED;
.LBB11_638:
	s_add_u32 s20, s18, 0xfff80080
	s_addc_u32 s21, s19, -1
	s_add_i32 s49, 0, 0x10000
	s_cmp_eq_u32 s48, 28
	s_cselect_b32 s23, s13, s21
	s_cselect_b32 s22, s44, s20
	v_add_u32_e32 v144, s49, v147
	s_cselect_b32 s21, s11, s47
	s_cselect_b32 s20, s45, s46
	s_add_i32 s52, 0, 0x14000
	ds_read_b128 v[150:153], v144
	ds_read_b128 v[154:157], v144 offset:1024
	ds_read_b128 v[158:161], v144 offset:2048
	ds_read_b128 v[162:165], v144 offset:3072
	v_add_u32_e32 v144, s52, v147
	ds_read_b128 v[166:169], v144
	ds_read_b128 v[170:173], v144 offset:1024
	ds_read_b128 v[174:177], v144 offset:2048
	ds_read_b128 v[178:181], v144 offset:3072
	v_lshl_add_u64 v[144:145], s[18:19], 0, v[140:141]
	s_add_i32 m0, s33, 0xc000
	ds_read_b128 v[198:201], v149
	ds_read_b128 v[202:205], v149 offset:1024
	ds_read_b128 v[220:223], v149 offset:2048
	ds_read_b128 v[224:227], v149 offset:3072
	ds_read_b128 v[228:231], v149 offset:4096
	ds_read_b128 v[232:235], v149 offset:5120
	ds_read_b128 v[236:239], v149 offset:6144
	ds_read_b128 v[240:243], v149 offset:7168
	global_load_lds_dwordx4 v[144:145], off
	v_lshl_add_u64 v[144:145], s[18:19], 0, v[142:143]
	s_add_i32 m0, s33, 0xe000
	s_nop 0
	global_load_lds_dwordx4 v[144:145], off
	s_waitcnt vmcnt(8)
	s_waitcnt lgkmcnt(0)
	s_barrier
	s_setprio 1
	s_waitcnt lgkmcnt(0)
	v_mfma_f32_16x16x32_bf16 v[128:131], v[150:153], v[198:201], v[128:131]
	v_mfma_f32_16x16x32_bf16 v[128:131], v[154:157], v[202:205], v[128:131]
	v_mfma_f32_16x16x32_bf16 v[120:123], v[150:153], v[220:223], v[120:123]
	v_mfma_f32_16x16x32_bf16 v[120:123], v[154:157], v[224:227], v[120:123]
	v_mfma_f32_16x16x32_bf16 v[104:107], v[150:153], v[228:231], v[104:107]
	v_mfma_f32_16x16x32_bf16 v[104:107], v[154:157], v[232:235], v[104:107]
	v_mfma_f32_16x16x32_bf16 v[88:91], v[150:153], v[236:239], v[88:91]
	v_mfma_f32_16x16x32_bf16 v[88:91], v[154:157], v[240:243], v[88:91]
	v_mfma_f32_16x16x32_bf16 v[124:127], v[158:161], v[198:201], v[124:127]
	v_mfma_f32_16x16x32_bf16 v[124:127], v[162:165], v[202:205], v[124:127]
	v_mfma_f32_16x16x32_bf16 v[112:115], v[158:161], v[220:223], v[112:115]
	v_mfma_f32_16x16x32_bf16 v[112:115], v[162:165], v[224:227], v[112:115]
	v_mfma_f32_16x16x32_bf16 v[96:99], v[158:161], v[228:231], v[96:99]
	v_mfma_f32_16x16x32_bf16 v[96:99], v[162:165], v[232:235], v[96:99]
	v_mfma_f32_16x16x32_bf16 v[80:83], v[158:161], v[236:239], v[80:83]
	v_mfma_f32_16x16x32_bf16 v[80:83], v[162:165], v[240:243], v[80:83]
	s_setprio 0
	s_setprio 1
	v_mfma_f32_16x16x32_bf16 v[116:119], v[166:169], v[198:201], v[116:119]
	v_mfma_f32_16x16x32_bf16 v[116:119], v[170:173], v[202:205], v[116:119]
	v_mfma_f32_16x16x32_bf16 v[100:103], v[166:169], v[220:223], v[100:103]
	v_mfma_f32_16x16x32_bf16 v[100:103], v[170:173], v[224:227], v[100:103]
	v_mfma_f32_16x16x32_bf16 v[84:87], v[166:169], v[228:231], v[84:87]
	v_mfma_f32_16x16x32_bf16 v[84:87], v[170:173], v[232:235], v[84:87]
	v_mfma_f32_16x16x32_bf16 v[72:75], v[166:169], v[236:239], v[72:75]
	v_mfma_f32_16x16x32_bf16 v[72:75], v[170:173], v[240:243], v[72:75]
	v_mfma_f32_16x16x32_bf16 v[108:111], v[174:177], v[198:201], v[108:111]
	v_mfma_f32_16x16x32_bf16 v[108:111], v[178:181], v[202:205], v[108:111]
	v_mfma_f32_16x16x32_bf16 v[92:95], v[174:177], v[220:223], v[92:95]
	v_mfma_f32_16x16x32_bf16 v[92:95], v[178:181], v[224:227], v[92:95]
	v_mfma_f32_16x16x32_bf16 v[76:79], v[174:177], v[228:231], v[76:79]
	v_mfma_f32_16x16x32_bf16 v[76:79], v[178:181], v[232:235], v[76:79]
	v_mfma_f32_16x16x32_bf16 v[68:71], v[174:177], v[236:239], v[68:71]
	v_mfma_f32_16x16x32_bf16 v[68:71], v[178:181], v[240:243], v[68:71]
	s_setprio 0
	s_barrier
	s_add_i32 s49, s49, s30
	v_lshl_add_u64 v[144:145], s[20:21], 0, v[2:3]
	s_mov_b32 m0, s49
	ds_read_b128 v[198:201], v149 offset:16384
	ds_read_b128 v[202:205], v149 offset:17408
	ds_read_b128 v[220:223], v149 offset:18432
	ds_read_b128 v[224:227], v149 offset:19456
	ds_read_b128 v[228:231], v149 offset:20480
	ds_read_b128 v[232:235], v149 offset:21504
	ds_read_b128 v[236:239], v149 offset:22528
	ds_read_b128 v[240:243], v149 offset:23552
	global_load_lds_dwordx4 v[144:145], off
	s_add_i32 m0, s49, 0x2000
	s_add_u32 s50, s20, 0x80000
	v_lshl_add_u64 v[184:185], s[20:21], 0, v[132:133]
	s_addc_u32 s51, s21, 0
	s_add_i32 s49, s52, s30
	global_load_lds_dwordx4 v[184:185], off
	v_lshl_add_u64 v[186:187], s[50:51], 0, v[2:3]
	s_mov_b32 m0, s49
	v_lshl_add_u64 v[196:197], s[22:23], 0, v[134:135]
	global_load_lds_dwordx4 v[186:187], off
	v_lshl_add_u64 v[186:187], s[50:51], 0, v[132:133]
	s_add_i32 m0, s49, 0x2000
	s_nop 0
	global_load_lds_dwordx4 v[186:187], off
	v_lshl_add_u64 v[186:187], s[22:23], 0, v[136:137]
	s_mov_b32 m0, s33
	s_nop 0
	global_load_lds_dwordx4 v[186:187], off
	s_mov_b32 m0, s36
	s_nop 0
	global_load_lds_dwordx4 v[196:197], off
	s_waitcnt vmcnt(8)
	s_waitcnt lgkmcnt(0)
	s_barrier
; #define PG8_STAGE(bufoff, gbase, voff) do { _Pragma("unroll") for (int _i = 0; _i < 2; ++_i) \
;         __builtin_amdgcn_global_load_lds((const unsigned*)((const char*)(gbase) + (voff)[_i]), (PG8_LAS unsigned*)(lds + (bufoff) + ldsw + _i * 8192), 16, 0, 0); } while (0)
; #define PG8_LDA(dst, b, h) do { _Pragma("unroll") for (int m = 0; m < 4; ++m) _Pragma("unroll") for (int k = 0; k < 2; ++k) dst[m][k] = *(const PG8_LAS bf16x8*)(lds + PG8_SA(b, h) + aoff + m * 2048 + k * 1024); } while (0)
; #define PG8_LDB(dst, b, h) do { _Pragma("unroll") for (int n = 0; n < 2; ++n) _Pragma("unroll") for (int k = 0; k < 2; ++k) dst[n][k] = *(const PG8_LAS bf16x8*)(lds + PG8_SB(b, h) + boff + n * 2048 + k * 1024); } while (0)
; #define PG8_MMA(ai, bj, At, Bt) do { __builtin_amdgcn_s_setprio(1); _Pragma("unroll") for (int m = 0; m < 4; ++m) _Pragma("unroll") for (int n = 0; n < 2; ++n) _Pragma("unroll") for (int k = 0; k < 2; ++k) \
;         acc[ai][bj][m][n] = __builtin_amdgcn_mfma_f32_16x16x32_bf16(Bt[n][k], At[m][k], acc[ai][bj][m][n], 0, 0, 0); __builtin_amdgcn_s_setprio(0); } while (0)
; #define PG8_WAIT_V(n) asm volatile("s_waitcnt vmcnt(" #n ")" ::: "memory")
; #define PG8_WAIT_L(n) asm volatile("s_waitcnt lgkmcnt(" #n ")" ::: "memory")
; #define PG8_BAR __builtin_amdgcn_s_barrier()
; #define PG8_SCHED __builtin_amdgcn_sched_barrier(0)
; template <class Epi, class Sched, bool ALIGN_EPI = false, bool SP2 = false>
; __device__ __forceinline__ void gemm_phase(PG8_LAS unsigned char* lds, const Gemm g, const Sched& S, const Epi& E) {
;     ...
;             PG8_WAIT_V(8); PG8_WAIT_L(0); PG8_BAR; PG8_MMA(1, 0, At, B0); PG8_MMA(1, 1, At, B1); PG8_BAR; PG8_SCHED;
;             PG8_LDB(B0, 1, 0); PG8_LDB(B1, 1, 1); PG8_SCHED; PG8_LDA(At, 1, 0); PG8_STAGE(PG8_SA(0, 1), a2 + hstep, voffA);
;             PG8_WAIT_V(8); PG8_WAIT_L(0); PG8_BAR; PG8_MMA(0, 0, At, B0); PG8_MMA(0, 1, At, B1); PG8_BAR; PG8_SCHED;
	s_setprio 1
	s_waitcnt lgkmcnt(0)
	v_mfma_f32_16x16x32_bf16 v[64:67], v[150:153], v[198:201], v[64:67]
	v_mfma_f32_16x16x32_bf16 v[64:67], v[154:157], v[202:205], v[64:67]
	v_mfma_f32_16x16x32_bf16 v[56:59], v[150:153], v[220:223], v[56:59]
	v_mfma_f32_16x16x32_bf16 v[56:59], v[154:157], v[224:227], v[56:59]
	v_mfma_f32_16x16x32_bf16 v[40:43], v[150:153], v[228:231], v[40:43]
	v_mfma_f32_16x16x32_bf16 v[40:43], v[154:157], v[232:235], v[40:43]
	v_mfma_f32_16x16x32_bf16 v[24:27], v[150:153], v[236:239], v[24:27]
	v_mfma_f32_16x16x32_bf16 v[24:27], v[154:157], v[240:243], v[24:27]
	v_mfma_f32_16x16x32_bf16 v[60:63], v[158:161], v[198:201], v[60:63]
	v_mfma_f32_16x16x32_bf16 v[60:63], v[162:165], v[202:205], v[60:63]
	v_mfma_f32_16x16x32_bf16 v[48:51], v[158:161], v[220:223], v[48:51]
	v_mfma_f32_16x16x32_bf16 v[48:51], v[162:165], v[224:227], v[48:51]
	v_mfma_f32_16x16x32_bf16 v[32:35], v[158:161], v[228:231], v[32:35]
	v_mfma_f32_16x16x32_bf16 v[32:35], v[162:165], v[232:235], v[32:35]
	v_mfma_f32_16x16x32_bf16 v[16:19], v[158:161], v[236:239], v[16:19]
	v_mfma_f32_16x16x32_bf16 v[16:19], v[162:165], v[240:243], v[16:19]
	s_setprio 0
	s_setprio 1
	v_mfma_f32_16x16x32_bf16 v[52:55], v[166:169], v[198:201], v[52:55]
	v_mfma_f32_16x16x32_bf16 v[52:55], v[170:173], v[202:205], v[52:55]
	v_mfma_f32_16x16x32_bf16 v[36:39], v[166:169], v[220:223], v[36:39]
	v_mfma_f32_16x16x32_bf16 v[36:39], v[170:173], v[224:227], v[36:39]
	v_mfma_f32_16x16x32_bf16 v[20:23], v[166:169], v[228:231], v[20:23]
	v_mfma_f32_16x16x32_bf16 v[20:23], v[170:173], v[232:235], v[20:23]
	v_mfma_f32_16x16x32_bf16 v[8:11], v[166:169], v[236:239], v[8:11]
	v_mfma_f32_16x16x32_bf16 v[8:11], v[170:173], v[240:243], v[8:11]
	v_mfma_f32_16x16x32_bf16 v[44:47], v[174:177], v[198:201], v[44:47]
	v_mfma_f32_16x16x32_bf16 v[44:47], v[178:181], v[202:205], v[44:47]
	v_mfma_f32_16x16x32_bf16 v[28:31], v[174:177], v[220:223], v[28:31]
	v_mfma_f32_16x16x32_bf16 v[28:31], v[178:181], v[224:227], v[28:31]
	v_mfma_f32_16x16x32_bf16 v[12:15], v[174:177], v[228:231], v[12:15]
	v_mfma_f32_16x16x32_bf16 v[12:15], v[178:181], v[232:235], v[12:15]
	v_mfma_f32_16x16x32_bf16 v[4:7], v[174:177], v[236:239], v[4:7]
	v_mfma_f32_16x16x32_bf16 v[4:7], v[178:181], v[240:243], v[4:7]
	s_setprio 0
	s_barrier
	s_add_i32 s49, 0, 0x18000
	s_add_i32 s50, 0, 0x1c000
	v_add_u32_e32 v162, s49, v147
	v_add_u32_e32 v178, s50, v147
	ds_read_b128 v[150:153], v162
	ds_read_b128 v[154:157], v162 offset:1024
	ds_read_b128 v[158:161], v162 offset:2048
	ds_read_b128 v[162:165], v162 offset:3072
	ds_read_b128 v[166:169], v178
	ds_read_b128 v[170:173], v178 offset:1024
	ds_read_b128 v[174:177], v178 offset:2048
	ds_read_b128 v[178:181], v178 offset:3072
	s_add_u32 s22, s22, 0x80000
	s_addc_u32 s23, s23, 0
	s_mov_b32 m0, s37
	v_lshl_add_u64 v[206:207], s[22:23], 0, v[136:137]
	ds_read_b128 v[198:201], v149 offset:32768
	ds_read_b128 v[202:205], v149 offset:33792
	ds_read_b128 v[220:223], v149 offset:34816
	ds_read_b128 v[224:227], v149 offset:35840
	ds_read_b128 v[228:231], v149 offset:36864
	ds_read_b128 v[232:235], v149 offset:37888
	ds_read_b128 v[236:239], v149 offset:38912
	ds_read_b128 v[240:243], v149 offset:39936
	global_load_lds_dwordx4 v[206:207], off
	v_lshl_add_u64 v[206:207], s[22:23], 0, v[134:135]
	s_mov_b32 m0, s38
	s_nop 0
	global_load_lds_dwordx4 v[206:207], off
	s_waitcnt vmcnt(8)
	s_waitcnt lgkmcnt(0)
	s_barrier
	s_setprio 1
	s_waitcnt lgkmcnt(0)
	v_mfma_f32_16x16x32_bf16 v[128:131], v[150:153], v[198:201], v[128:131]
	v_mfma_f32_16x16x32_bf16 v[128:131], v[154:157], v[202:205], v[128:131]
	v_mfma_f32_16x16x32_bf16 v[120:123], v[150:153], v[220:223], v[120:123]
	v_mfma_f32_16x16x32_bf16 v[120:123], v[154:157], v[224:227], v[120:123]
	v_mfma_f32_16x16x32_bf16 v[104:107], v[150:153], v[228:231], v[104:107]
	v_mfma_f32_16x16x32_bf16 v[104:107], v[154:157], v[232:235], v[104:107]
	v_mfma_f32_16x16x32_bf16 v[88:91], v[150:153], v[236:239], v[88:91]
	v_mfma_f32_16x16x32_bf16 v[88:91], v[154:157], v[240:243], v[88:91]
	v_mfma_f32_16x16x32_bf16 v[124:127], v[158:161], v[198:201], v[124:127]
	v_mfma_f32_16x16x32_bf16 v[124:127], v[162:165], v[202:205], v[124:127]
	v_mfma_f32_16x16x32_bf16 v[112:115], v[158:161], v[220:223], v[112:115]
	v_mfma_f32_16x16x32_bf16 v[112:115], v[162:165], v[224:227], v[112:115]
	v_mfma_f32_16x16x32_bf16 v[96:99], v[158:161], v[228:231], v[96:99]
	v_mfma_f32_16x16x32_bf16 v[96:99], v[162:165], v[232:235], v[96:99]
	v_mfma_f32_16x16x32_bf16 v[80:83], v[158:161], v[236:239], v[80:83]
	v_mfma_f32_16x16x32_bf16 v[80:83], v[162:165], v[240:243], v[80:83]
	s_setprio 0
	s_setprio 1
	v_mfma_f32_16x16x32_bf16 v[116:119], v[166:169], v[198:201], v[116:119]
	v_mfma_f32_16x16x32_bf16 v[116:119], v[170:173], v[202:205], v[116:119]
	v_mfma_f32_16x16x32_bf16 v[100:103], v[166:169], v[220:223], v[100:103]
	v_mfma_f32_16x16x32_bf16 v[100:103], v[170:173], v[224:227], v[100:103]
	v_mfma_f32_16x16x32_bf16 v[84:87], v[166:169], v[228:231], v[84:87]
	v_mfma_f32_16x16x32_bf16 v[84:87], v[170:173], v[232:235], v[84:87]
	v_mfma_f32_16x16x32_bf16 v[72:75], v[166:169], v[236:239], v[72:75]
	v_mfma_f32_16x16x32_bf16 v[72:75], v[170:173], v[240:243], v[72:75]
	v_mfma_f32_16x16x32_bf16 v[108:111], v[174:177], v[198:201], v[108:111]
	v_mfma_f32_16x16x32_bf16 v[108:111], v[178:181], v[202:205], v[108:111]
	v_mfma_f32_16x16x32_bf16 v[92:95], v[174:177], v[220:223], v[92:95]
	v_mfma_f32_16x16x32_bf16 v[92:95], v[178:181], v[224:227], v[92:95]
	v_mfma_f32_16x16x32_bf16 v[76:79], v[174:177], v[228:231], v[76:79]
	v_mfma_f32_16x16x32_bf16 v[76:79], v[178:181], v[232:235], v[76:79]
	v_mfma_f32_16x16x32_bf16 v[68:71], v[174:177], v[236:239], v[68:71]
	v_mfma_f32_16x16x32_bf16 v[68:71], v[178:181], v[240:243], v[68:71]
	s_setprio 0
	s_barrier
; #define PG8_STAGE(bufoff, gbase, voff) do { _Pragma("unroll") for (int _i = 0; _i < 2; ++_i) \
;         __builtin_amdgcn_global_load_lds((const unsigned*)((const char*)(gbase) + (voff)[_i]), (PG8_LAS unsigned*)(lds + (bufoff) + ldsw + _i * 8192), 16, 0, 0); } while (0)
; #define PG8_LDA(dst, b, h) do { _Pragma("unroll") for (int m = 0; m < 4; ++m) _Pragma("unroll") for (int k = 0; k < 2; ++k) dst[m][k] = *(const PG8_LAS bf16x8*)(lds + PG8_SA(b, h) + aoff + m * 2048 + k * 1024); } while (0)
; #define PG8_MMA(ai, bj, At, Bt) do { __builtin_amdgcn_s_setprio(1); _Pragma("unroll") for (int m = 0; m < 4; ++m) _Pragma("unroll") for (int n = 0; n < 2; ++n) _Pragma("unroll") for (int k = 0; k < 2; ++k) \
;         acc[ai][bj][m][n] = __builtin_amdgcn_mfma_f32_16x16x32_bf16(Bt[n][k], At[m][k], acc[ai][bj][m][n], 0, 0, 0); __builtin_amdgcn_s_setprio(0); } while (0)
; #define PG8_WAIT_V(n) asm volatile("s_waitcnt vmcnt(" #n ")" ::: "memory")
; #define PG8_WAIT_L(n) asm volatile("s_waitcnt lgkmcnt(" #n ")" ::: "memory")
; #define PG8_BAR __builtin_amdgcn_s_barrier()
; #define PG8_SCHED __builtin_amdgcn_sched_barrier(0)
; template <class Epi, class Sched, bool ALIGN_EPI = false, bool SP2 = false>
; __device__ __forceinline__ void gemm_phase(PG8_LAS unsigned char* lds, const Gemm g, const Sched& S, const Epi& E) {
;     ...
;             PG8_LDA(At, 1, 1); PG8_STAGE(PG8_SB(1, 0), b3, voffB); PG8_STAGE(PG8_SB(1, 1), b3 + hstep, voffB); PG8_STAGE(PG8_SA(1, 0), a3, voffA);
;             PG8_WAIT_V(8); PG8_WAIT_L(0); PG8_BAR; PG8_MMA(1, 0, At, B0); PG8_MMA(1, 1, At, B1); PG8_BAR; PG8_SCHED;
	s_add_i32 s22, s49, s30
	v_lshl_add_u64 v[144:145], v[144:145], 0, s[34:35]
	s_mov_b32 m0, s22
	ds_read_b128 v[198:201], v149 offset:49152
	ds_read_b128 v[202:205], v149 offset:50176
	ds_read_b128 v[220:223], v149 offset:51200
	ds_read_b128 v[224:227], v149 offset:52224
	ds_read_b128 v[228:231], v149 offset:53248
	ds_read_b128 v[232:235], v149 offset:54272
	ds_read_b128 v[236:239], v149 offset:55296
	ds_read_b128 v[240:243], v149 offset:56320
	global_load_lds_dwordx4 v[144:145], off
	s_add_i32 m0, s22, 0x2000
	s_add_u32 s20, s20, 0x80080
	v_lshl_add_u64 v[144:145], v[184:185], 0, s[34:35]
	s_addc_u32 s21, s21, 0
	s_add_i32 s22, s50, s30
	global_load_lds_dwordx4 v[144:145], off
	v_lshl_add_u64 v[144:145], s[20:21], 0, v[2:3]
	s_mov_b32 m0, s22
	s_nop 0
	global_load_lds_dwordx4 v[144:145], off
	v_lshl_add_u64 v[144:145], s[20:21], 0, v[132:133]
	s_add_i32 m0, s22, 0x2000
	s_nop 0
	global_load_lds_dwordx4 v[144:145], off
	v_lshl_add_u64 v[144:145], v[186:187], 0, s[34:35]
	s_mov_b32 m0, s39
	s_nop 0
	global_load_lds_dwordx4 v[144:145], off
	v_lshl_add_u64 v[144:145], v[196:197], 0, s[34:35]
	s_mov_b32 m0, s40
	s_nop 0
	global_load_lds_dwordx4 v[144:145], off
	s_waitcnt vmcnt(8)
	s_waitcnt lgkmcnt(0)
	s_barrier
	s_setprio 1
	s_waitcnt lgkmcnt(0)
	v_mfma_f32_16x16x32_bf16 v[64:67], v[150:153], v[198:201], v[64:67]
	v_mfma_f32_16x16x32_bf16 v[64:67], v[154:157], v[202:205], v[64:67]
	v_mfma_f32_16x16x32_bf16 v[56:59], v[150:153], v[220:223], v[56:59]
	v_mfma_f32_16x16x32_bf16 v[56:59], v[154:157], v[224:227], v[56:59]
	v_mfma_f32_16x16x32_bf16 v[40:43], v[150:153], v[228:231], v[40:43]
	v_mfma_f32_16x16x32_bf16 v[40:43], v[154:157], v[232:235], v[40:43]
	v_mfma_f32_16x16x32_bf16 v[24:27], v[150:153], v[236:239], v[24:27]
	v_mfma_f32_16x16x32_bf16 v[24:27], v[154:157], v[240:243], v[24:27]
	v_mfma_f32_16x16x32_bf16 v[60:63], v[158:161], v[198:201], v[60:63]
	v_mfma_f32_16x16x32_bf16 v[60:63], v[162:165], v[202:205], v[60:63]
	v_mfma_f32_16x16x32_bf16 v[48:51], v[158:161], v[220:223], v[48:51]
	v_mfma_f32_16x16x32_bf16 v[48:51], v[162:165], v[224:227], v[48:51]
	v_mfma_f32_16x16x32_bf16 v[32:35], v[158:161], v[228:231], v[32:35]
	v_mfma_f32_16x16x32_bf16 v[32:35], v[162:165], v[232:235], v[32:35]
	v_mfma_f32_16x16x32_bf16 v[16:19], v[158:161], v[236:239], v[16:19]
	v_mfma_f32_16x16x32_bf16 v[16:19], v[162:165], v[240:243], v[16:19]
	s_setprio 0
	s_setprio 1
	v_mfma_f32_16x16x32_bf16 v[52:55], v[166:169], v[198:201], v[52:55]
	v_mfma_f32_16x16x32_bf16 v[52:55], v[170:173], v[202:205], v[52:55]
	v_mfma_f32_16x16x32_bf16 v[36:39], v[166:169], v[220:223], v[36:39]
	v_mfma_f32_16x16x32_bf16 v[36:39], v[170:173], v[224:227], v[36:39]
	v_mfma_f32_16x16x32_bf16 v[20:23], v[166:169], v[228:231], v[20:23]
	v_mfma_f32_16x16x32_bf16 v[20:23], v[170:173], v[232:235], v[20:23]
	v_mfma_f32_16x16x32_bf16 v[8:11], v[166:169], v[236:239], v[8:11]
	v_mfma_f32_16x16x32_bf16 v[8:11], v[170:173], v[240:243], v[8:11]
	v_mfma_f32_16x16x32_bf16 v[44:47], v[174:177], v[198:201], v[44:47]
	v_mfma_f32_16x16x32_bf16 v[44:47], v[178:181], v[202:205], v[44:47]
	v_mfma_f32_16x16x32_bf16 v[28:31], v[174:177], v[220:223], v[28:31]
	v_mfma_f32_16x16x32_bf16 v[28:31], v[178:181], v[224:227], v[28:31]
	v_mfma_f32_16x16x32_bf16 v[12:15], v[174:177], v[228:231], v[12:15]
	v_mfma_f32_16x16x32_bf16 v[12:15], v[178:181], v[232:235], v[12:15]
	v_mfma_f32_16x16x32_bf16 v[4:7], v[174:177], v[236:239], v[4:7]
	v_mfma_f32_16x16x32_bf16 v[4:7], v[178:181], v[240:243], v[4:7]
	s_setprio 0
	s_barrier
	s_add_i32 s48, s48, 2
	s_add_u32 s18, s18, 0x100
	s_addc_u32 s19, s19, 0
	s_add_u32 s46, s46, 0x100
	s_addc_u32 s47, s47, 0
	s_cmp_gt_u32 s48, 29
	s_cbranch_scc0 .LBB11_638
	s_and_b64 vcc, exec, s[4:5]
	s_cbranch_vccz .LBB11_641
	s_barrier

; #define PG8_STAGE(bufoff, gbase, voff) do { _Pragma("unroll") for (int _i = 0; _i < 2; ++_i) \
;         __builtin_amdgcn_global_load_lds((const unsigned*)((const char*)(gbase) + (voff)[_i]), (PG8_LAS unsigned*)(lds + (bufoff) + ldsw + _i * 8192), 16, 0, 0); } while (0)
; #define PG8_LDA(dst, b, h) do { _Pragma("unroll") for (int m = 0; m < 4; ++m) _Pragma("unroll") for (int k = 0; k < 2; ++k) dst[m][k] = *(const PG8_LAS bf16x8*)(lds + PG8_SA(b, h) + aoff + m * 2048 + k * 1024); } while (0)
; #define PG8_LDB(dst, b, h) do { _Pragma("unroll") for (int n = 0; n < 2; ++n) _Pragma("unroll") for (int k = 0; k < 2; ++k) dst[n][k] = *(const PG8_LAS bf16x8*)(lds + PG8_SB(b, h) + boff + n * 2048 + k * 1024); } while (0)
; #define PG8_MMA(ai, bj, At, Bt) do { __builtin_amdgcn_s_setprio(1); _Pragma("unroll") for (int m = 0; m < 4; ++m) _Pragma("unroll") for (int n = 0; n < 2; ++n) _Pragma("unroll") for (int k = 0; k < 2; ++k) \
;         acc[ai][bj][m][n] = __builtin_amdgcn_mfma_f32_16x16x32_bf16(Bt[n][k], At[m][k], acc[ai][bj][m][n], 0, 0, 0); __builtin_amdgcn_s_setprio(0); } while (0)
; #define PG8_WAIT_V(n) asm volatile("s_waitcnt vmcnt(" #n ")" ::: "memory")
; #define PG8_WAIT_L(n) asm volatile("s_waitcnt lgkmcnt(" #n ")" ::: "memory")
; #define PG8_BAR __builtin_amdgcn_s_barrier()
; #define PG8_SCHED __builtin_amdgcn_sched_barrier(0)
; template <class Epi, class Sched, bool ALIGN_EPI = false, bool SP2 = false>
; __device__ __forceinline__ void gemm_phase(PG8_LAS unsigned char* lds, const Gemm g, const Sched& S, const Epi& E) {
;     ...
;             const char* a2 = last ? nA : cA + (size_t)(t + 2) * kstep; const char* b2 = last ? nB : cB + (size_t)(t + 2) * kstep;
;             const char* a3 = a2 + kstep; const char* b3 = b2 + kstep;
;             if (last && has_next) S.a_ready(nxt);
;             if constexpr (SP2) {
;             PG8_LDB(B0, 0, 0); PG8_LDB(B1, 0, 1); PG8_SCHED; PG8_LDA(At, 0, 0); PG8_STAGE(PG8_SA(1, 1), a1 + hstep, voffA);
;             PG8_WAIT_V(8); PG8_WAIT_L(0); PG8_BAR; PG8_MMA(0, 0, At, B0); PG8_MMA(0, 1, At, B1); PG8_BAR; PG8_SCHED;
;             PG8_LDA(At, 0, 1); PG8_STAGE(PG8_SB(0, 0), b2, voffB); PG8_STAGE(PG8_SB(0, 1), b2 + hstep, voffB); PG8_STAGE(PG8_SA(0, 0), a2, voffA);
;             PG8_WAIT_V(8); PG8_WAIT_L(0); PG8_BAR; PG8_MMA(1, 0, At, B0); PG8_MMA(1, 1, At, B1); PG8_BAR; PG8_SCHED;
.LBB11_913:
	s_add_u32 s16, s14, 0xfff80080
	s_addc_u32 s17, s15, -1
	s_add_i32 s44, 0, 0x10000
	s_cmp_eq_u32 s43, 28
	s_cselect_b32 s19, s9, s17
	s_cselect_b32 s18, s37, s16
	v_add_u32_e32 v144, s44, v146
	s_cselect_b32 s17, s7, s42
	s_cselect_b32 s16, s40, s41
	s_add_i32 s46, 0, 0x14000
	ds_read_b128 v[150:153], v144
	ds_read_b128 v[154:157], v144 offset:1024
	ds_read_b128 v[158:161], v144 offset:2048
	ds_read_b128 v[162:165], v144 offset:3072
	v_add_u32_e32 v144, s46, v146
	ds_read_b128 v[166:169], v144
	ds_read_b128 v[170:173], v144 offset:1024
	ds_read_b128 v[174:177], v144 offset:2048
	ds_read_b128 v[178:181], v144 offset:3072
	v_lshl_add_u64 v[144:145], s[14:15], 0, v[140:141]
	s_add_i32 m0, s24, 0xc000
	ds_read_b128 v[198:201], v148
	ds_read_b128 v[202:205], v148 offset:1024
	ds_read_b128 v[220:223], v148 offset:2048
	ds_read_b128 v[224:227], v148 offset:3072
	ds_read_b128 v[228:231], v148 offset:4096
	ds_read_b128 v[232:235], v148 offset:5120
	ds_read_b128 v[236:239], v148 offset:6144
	ds_read_b128 v[240:243], v148 offset:7168
	global_load_lds_dwordx4 v[144:145], off
	v_lshl_add_u64 v[144:145], s[14:15], 0, v[142:143]
	s_add_i32 m0, s24, 0xe000
	s_nop 0
	global_load_lds_dwordx4 v[144:145], off
	s_waitcnt vmcnt(8)
	s_waitcnt lgkmcnt(0)
	s_barrier
	s_setprio 1
	s_waitcnt lgkmcnt(0)
	v_mfma_f32_16x16x32_bf16 v[128:131], v[150:153], v[198:201], v[128:131]
	v_mfma_f32_16x16x32_bf16 v[128:131], v[154:157], v[202:205], v[128:131]
	v_mfma_f32_16x16x32_bf16 v[120:123], v[150:153], v[220:223], v[120:123]
	v_mfma_f32_16x16x32_bf16 v[120:123], v[154:157], v[224:227], v[120:123]
	v_mfma_f32_16x16x32_bf16 v[104:107], v[150:153], v[228:231], v[104:107]
	v_mfma_f32_16x16x32_bf16 v[104:107], v[154:157], v[232:235], v[104:107]
	v_mfma_f32_16x16x32_bf16 v[88:91], v[150:153], v[236:239], v[88:91]
	v_mfma_f32_16x16x32_bf16 v[88:91], v[154:157], v[240:243], v[88:91]
	v_mfma_f32_16x16x32_bf16 v[124:127], v[158:161], v[198:201], v[124:127]
	v_mfma_f32_16x16x32_bf16 v[124:127], v[162:165], v[202:205], v[124:127]
	v_mfma_f32_16x16x32_bf16 v[112:115], v[158:161], v[220:223], v[112:115]
	v_mfma_f32_16x16x32_bf16 v[112:115], v[162:165], v[224:227], v[112:115]
	v_mfma_f32_16x16x32_bf16 v[96:99], v[158:161], v[228:231], v[96:99]
	v_mfma_f32_16x16x32_bf16 v[96:99], v[162:165], v[232:235], v[96:99]
	v_mfma_f32_16x16x32_bf16 v[80:83], v[158:161], v[236:239], v[80:83]
	v_mfma_f32_16x16x32_bf16 v[80:83], v[162:165], v[240:243], v[80:83]
	s_setprio 0
	s_setprio 1
	v_mfma_f32_16x16x32_bf16 v[116:119], v[166:169], v[198:201], v[116:119]
	v_mfma_f32_16x16x32_bf16 v[116:119], v[170:173], v[202:205], v[116:119]
	v_mfma_f32_16x16x32_bf16 v[100:103], v[166:169], v[220:223], v[100:103]
	v_mfma_f32_16x16x32_bf16 v[100:103], v[170:173], v[224:227], v[100:103]
	v_mfma_f32_16x16x32_bf16 v[84:87], v[166:169], v[228:231], v[84:87]
	v_mfma_f32_16x16x32_bf16 v[84:87], v[170:173], v[232:235], v[84:87]
	v_mfma_f32_16x16x32_bf16 v[72:75], v[166:169], v[236:239], v[72:75]
	v_mfma_f32_16x16x32_bf16 v[72:75], v[170:173], v[240:243], v[72:75]
	v_mfma_f32_16x16x32_bf16 v[108:111], v[174:177], v[198:201], v[108:111]
	v_mfma_f32_16x16x32_bf16 v[108:111], v[178:181], v[202:205], v[108:111]
	v_mfma_f32_16x16x32_bf16 v[92:95], v[174:177], v[220:223], v[92:95]
	v_mfma_f32_16x16x32_bf16 v[92:95], v[178:181], v[224:227], v[92:95]
	v_mfma_f32_16x16x32_bf16 v[76:79], v[174:177], v[228:231], v[76:79]
	v_mfma_f32_16x16x32_bf16 v[76:79], v[178:181], v[232:235], v[76:79]
	v_mfma_f32_16x16x32_bf16 v[68:71], v[174:177], v[236:239], v[68:71]
	v_mfma_f32_16x16x32_bf16 v[68:71], v[178:181], v[240:243], v[68:71]
	s_setprio 0
	s_barrier
	s_add_i32 s44, s44, s23
	v_lshl_add_u64 v[144:145], s[16:17], 0, v[2:3]
	s_mov_b32 m0, s44
	ds_read_b128 v[198:201], v148 offset:16384
	ds_read_b128 v[202:205], v148 offset:17408
	ds_read_b128 v[220:223], v148 offset:18432
	ds_read_b128 v[224:227], v148 offset:19456
	ds_read_b128 v[228:231], v148 offset:20480
	ds_read_b128 v[232:235], v148 offset:21504
	ds_read_b128 v[236:239], v148 offset:22528
	ds_read_b128 v[240:243], v148 offset:23552
	global_load_lds_dwordx4 v[144:145], off
	s_add_i32 m0, s44, 0x2000
	s_add_u32 s44, s16, 0x80000
	v_lshl_add_u64 v[184:185], s[16:17], 0, v[132:133]
	s_addc_u32 s45, s17, 0
	s_add_i32 s46, s46, s23
	global_load_lds_dwordx4 v[184:185], off
	v_lshl_add_u64 v[186:187], s[44:45], 0, v[2:3]
	s_mov_b32 m0, s46
	v_lshl_add_u64 v[196:197], s[18:19], 0, v[134:135]
	global_load_lds_dwordx4 v[186:187], off
	v_lshl_add_u64 v[186:187], s[44:45], 0, v[132:133]
	s_add_i32 m0, s46, 0x2000
	s_nop 0
	global_load_lds_dwordx4 v[186:187], off
	v_lshl_add_u64 v[186:187], s[18:19], 0, v[136:137]
	s_mov_b32 m0, s24
	s_nop 0
	global_load_lds_dwordx4 v[186:187], off
	s_mov_b32 m0, s25
	s_nop 0
	global_load_lds_dwordx4 v[196:197], off
	s_waitcnt vmcnt(8)
	s_waitcnt lgkmcnt(0)
	s_barrier
; #define PG8_STAGE(bufoff, gbase, voff) do { _Pragma("unroll") for (int _i = 0; _i < 2; ++_i) \
;         __builtin_amdgcn_global_load_lds((const unsigned*)((const char*)(gbase) + (voff)[_i]), (PG8_LAS unsigned*)(lds + (bufoff) + ldsw + _i * 8192), 16, 0, 0); } while (0)
; #define PG8_LDA(dst, b, h) do { _Pragma("unroll") for (int m = 0; m < 4; ++m) _Pragma("unroll") for (int k = 0; k < 2; ++k) dst[m][k] = *(const PG8_LAS bf16x8*)(lds + PG8_SA(b, h) + aoff + m * 2048 + k * 1024); } while (0)
; #define PG8_LDB(dst, b, h) do { _Pragma("unroll") for (int n = 0; n < 2; ++n) _Pragma("unroll") for (int k = 0; k < 2; ++k) dst[n][k] = *(const PG8_LAS bf16x8*)(lds + PG8_SB(b, h) + boff + n * 2048 + k * 1024); } while (0)
; #define PG8_MMA(ai, bj, At, Bt) do { __builtin_amdgcn_s_setprio(1); _Pragma("unroll") for (int m = 0; m < 4; ++m) _Pragma("unroll") for (int n = 0; n < 2; ++n) _Pragma("unroll") for (int k = 0; k < 2; ++k) \
;         acc[ai][bj][m][n] = __builtin_amdgcn_mfma_f32_16x16x32_bf16(Bt[n][k], At[m][k], acc[ai][bj][m][n], 0, 0, 0); __builtin_amdgcn_s_setprio(0); } while (0)
; #define PG8_WAIT_V(n) asm volatile("s_waitcnt vmcnt(" #n ")" ::: "memory")
; #define PG8_WAIT_L(n) asm volatile("s_waitcnt lgkmcnt(" #n ")" ::: "memory")
; #define PG8_BAR __builtin_amdgcn_s_barrier()
; #define PG8_SCHED __builtin_amdgcn_sched_barrier(0)
; template <class Epi, class Sched, bool ALIGN_EPI = false, bool SP2 = false>
; __device__ __forceinline__ void gemm_phase(PG8_LAS unsigned char* lds, const Gemm g, const Sched& S, const Epi& E) {
;     ...
;             PG8_WAIT_V(8); PG8_WAIT_L(0); PG8_BAR; PG8_MMA(1, 0, At, B0); PG8_MMA(1, 1, At, B1); PG8_BAR; PG8_SCHED;
;             PG8_LDB(B0, 1, 0); PG8_LDB(B1, 1, 1); PG8_SCHED; PG8_LDA(At, 1, 0); PG8_STAGE(PG8_SA(0, 1), a2 + hstep, voffA);
;             PG8_WAIT_V(8); PG8_WAIT_L(0); PG8_BAR; PG8_MMA(0, 0, At, B0); PG8_MMA(0, 1, At, B1); PG8_BAR; PG8_SCHED;
	s_setprio 1
	s_waitcnt lgkmcnt(0)
	v_mfma_f32_16x16x32_bf16 v[64:67], v[150:153], v[198:201], v[64:67]
	v_mfma_f32_16x16x32_bf16 v[64:67], v[154:157], v[202:205], v[64:67]
	v_mfma_f32_16x16x32_bf16 v[56:59], v[150:153], v[220:223], v[56:59]
	v_mfma_f32_16x16x32_bf16 v[56:59], v[154:157], v[224:227], v[56:59]
	v_mfma_f32_16x16x32_bf16 v[40:43], v[150:153], v[228:231], v[40:43]
	v_mfma_f32_16x16x32_bf16 v[40:43], v[154:157], v[232:235], v[40:43]
	v_mfma_f32_16x16x32_bf16 v[24:27], v[150:153], v[236:239], v[24:27]
	v_mfma_f32_16x16x32_bf16 v[24:27], v[154:157], v[240:243], v[24:27]
	v_mfma_f32_16x16x32_bf16 v[60:63], v[158:161], v[198:201], v[60:63]
	v_mfma_f32_16x16x32_bf16 v[60:63], v[162:165], v[202:205], v[60:63]
	v_mfma_f32_16x16x32_bf16 v[48:51], v[158:161], v[220:223], v[48:51]
	v_mfma_f32_16x16x32_bf16 v[48:51], v[162:165], v[224:227], v[48:51]
	v_mfma_f32_16x16x32_bf16 v[32:35], v[158:161], v[228:231], v[32:35]
	v_mfma_f32_16x16x32_bf16 v[32:35], v[162:165], v[232:235], v[32:35]
	v_mfma_f32_16x16x32_bf16 v[16:19], v[158:161], v[236:239], v[16:19]
	v_mfma_f32_16x16x32_bf16 v[16:19], v[162:165], v[240:243], v[16:19]
	s_setprio 0
	s_setprio 1
	v_mfma_f32_16x16x32_bf16 v[52:55], v[166:169], v[198:201], v[52:55]
	v_mfma_f32_16x16x32_bf16 v[52:55], v[170:173], v[202:205], v[52:55]
	v_mfma_f32_16x16x32_bf16 v[36:39], v[166:169], v[220:223], v[36:39]
	v_mfma_f32_16x16x32_bf16 v[36:39], v[170:173], v[224:227], v[36:39]
	v_mfma_f32_16x16x32_bf16 v[20:23], v[166:169], v[228:231], v[20:23]
	v_mfma_f32_16x16x32_bf16 v[20:23], v[170:173], v[232:235], v[20:23]
	v_mfma_f32_16x16x32_bf16 v[8:11], v[166:169], v[236:239], v[8:11]
	v_mfma_f32_16x16x32_bf16 v[8:11], v[170:173], v[240:243], v[8:11]
	v_mfma_f32_16x16x32_bf16 v[44:47], v[174:177], v[198:201], v[44:47]
	v_mfma_f32_16x16x32_bf16 v[44:47], v[178:181], v[202:205], v[44:47]
	v_mfma_f32_16x16x32_bf16 v[28:31], v[174:177], v[220:223], v[28:31]
	v_mfma_f32_16x16x32_bf16 v[28:31], v[178:181], v[224:227], v[28:31]
	v_mfma_f32_16x16x32_bf16 v[12:15], v[174:177], v[228:231], v[12:15]
	v_mfma_f32_16x16x32_bf16 v[12:15], v[178:181], v[232:235], v[12:15]
	v_mfma_f32_16x16x32_bf16 v[4:7], v[174:177], v[236:239], v[4:7]
	v_mfma_f32_16x16x32_bf16 v[4:7], v[178:181], v[240:243], v[4:7]
	s_setprio 0
	s_barrier
	s_add_i32 s44, 0, 0x18000
	v_add_u32_e32 v149, s44, v146
	s_add_i32 s45, 0, 0x1c000
	ds_read_b128 v[150:153], v149
	ds_read_b128 v[154:157], v149 offset:1024
	ds_read_b128 v[158:161], v149 offset:2048
	ds_read_b128 v[162:165], v149 offset:3072
	v_add_u32_e32 v149, s45, v146
	ds_read_b128 v[166:169], v149
	ds_read_b128 v[170:173], v149 offset:1024
	ds_read_b128 v[174:177], v149 offset:2048
	ds_read_b128 v[178:181], v149 offset:3072
	s_add_u32 s18, s18, 0x80000
	s_addc_u32 s19, s19, 0
	s_mov_b32 m0, s26
	v_lshl_add_u64 v[206:207], s[18:19], 0, v[136:137]
	ds_read_b128 v[198:201], v148 offset:32768
	ds_read_b128 v[202:205], v148 offset:33792
	ds_read_b128 v[220:223], v148 offset:34816
	ds_read_b128 v[224:227], v148 offset:35840
	ds_read_b128 v[228:231], v148 offset:36864
	ds_read_b128 v[232:235], v148 offset:37888
	ds_read_b128 v[236:239], v148 offset:38912
	ds_read_b128 v[240:243], v148 offset:39936
	global_load_lds_dwordx4 v[206:207], off
	v_lshl_add_u64 v[206:207], s[18:19], 0, v[134:135]
	s_mov_b32 m0, s27
	s_nop 0
	global_load_lds_dwordx4 v[206:207], off
	s_waitcnt vmcnt(8)
	s_waitcnt lgkmcnt(0)
	s_barrier
	s_setprio 1
	s_waitcnt lgkmcnt(0)
	v_mfma_f32_16x16x32_bf16 v[128:131], v[150:153], v[198:201], v[128:131]
	v_mfma_f32_16x16x32_bf16 v[128:131], v[154:157], v[202:205], v[128:131]
	v_mfma_f32_16x16x32_bf16 v[120:123], v[150:153], v[220:223], v[120:123]
	v_mfma_f32_16x16x32_bf16 v[120:123], v[154:157], v[224:227], v[120:123]
	v_mfma_f32_16x16x32_bf16 v[104:107], v[150:153], v[228:231], v[104:107]
	v_mfma_f32_16x16x32_bf16 v[104:107], v[154:157], v[232:235], v[104:107]
	v_mfma_f32_16x16x32_bf16 v[88:91], v[150:153], v[236:239], v[88:91]
	v_mfma_f32_16x16x32_bf16 v[88:91], v[154:157], v[240:243], v[88:91]
	v_mfma_f32_16x16x32_bf16 v[124:127], v[158:161], v[198:201], v[124:127]
	v_mfma_f32_16x16x32_bf16 v[124:127], v[162:165], v[202:205], v[124:127]
	v_mfma_f32_16x16x32_bf16 v[112:115], v[158:161], v[220:223], v[112:115]
	v_mfma_f32_16x16x32_bf16 v[112:115], v[162:165], v[224:227], v[112:115]
	v_mfma_f32_16x16x32_bf16 v[96:99], v[158:161], v[228:231], v[96:99]
	v_mfma_f32_16x16x32_bf16 v[96:99], v[162:165], v[232:235], v[96:99]
	v_mfma_f32_16x16x32_bf16 v[80:83], v[158:161], v[236:239], v[80:83]
	v_mfma_f32_16x16x32_bf16 v[80:83], v[162:165], v[240:243], v[80:83]
	s_setprio 0
	s_setprio 1
	v_mfma_f32_16x16x32_bf16 v[116:119], v[166:169], v[198:201], v[116:119]
	v_mfma_f32_16x16x32_bf16 v[116:119], v[170:173], v[202:205], v[116:119]
	v_mfma_f32_16x16x32_bf16 v[100:103], v[166:169], v[220:223], v[100:103]
	v_mfma_f32_16x16x32_bf16 v[100:103], v[170:173], v[224:227], v[100:103]
	v_mfma_f32_16x16x32_bf16 v[84:87], v[166:169], v[228:231], v[84:87]
	v_mfma_f32_16x16x32_bf16 v[84:87], v[170:173], v[232:235], v[84:87]
	v_mfma_f32_16x16x32_bf16 v[72:75], v[166:169], v[236:239], v[72:75]
	v_mfma_f32_16x16x32_bf16 v[72:75], v[170:173], v[240:243], v[72:75]
	v_mfma_f32_16x16x32_bf16 v[108:111], v[174:177], v[198:201], v[108:111]
	v_mfma_f32_16x16x32_bf16 v[108:111], v[178:181], v[202:205], v[108:111]
	v_mfma_f32_16x16x32_bf16 v[92:95], v[174:177], v[220:223], v[92:95]
	v_mfma_f32_16x16x32_bf16 v[92:95], v[178:181], v[224:227], v[92:95]
	v_mfma_f32_16x16x32_bf16 v[76:79], v[174:177], v[228:231], v[76:79]
	v_mfma_f32_16x16x32_bf16 v[76:79], v[178:181], v[232:235], v[76:79]
	v_mfma_f32_16x16x32_bf16 v[68:71], v[174:177], v[236:239], v[68:71]
	v_mfma_f32_16x16x32_bf16 v[68:71], v[178:181], v[240:243], v[68:71]
	s_setprio 0
	s_barrier
; #define PG8_STAGE(bufoff, gbase, voff) do { _Pragma("unroll") for (int _i = 0; _i < 2; ++_i) \
;         __builtin_amdgcn_global_load_lds((const unsigned*)((const char*)(gbase) + (voff)[_i]), (PG8_LAS unsigned*)(lds + (bufoff) + ldsw + _i * 8192), 16, 0, 0); } while (0)
; #define PG8_LDA(dst, b, h) do { _Pragma("unroll") for (int m = 0; m < 4; ++m) _Pragma("unroll") for (int k = 0; k < 2; ++k) dst[m][k] = *(const PG8_LAS bf16x8*)(lds + PG8_SA(b, h) + aoff + m * 2048 + k * 1024); } while (0)
; #define PG8_MMA(ai, bj, At, Bt) do { __builtin_amdgcn_s_setprio(1); _Pragma("unroll") for (int m = 0; m < 4; ++m) _Pragma("unroll") for (int n = 0; n < 2; ++n) _Pragma("unroll") for (int k = 0; k < 2; ++k) \
;         acc[ai][bj][m][n] = __builtin_amdgcn_mfma_f32_16x16x32_bf16(Bt[n][k], At[m][k], acc[ai][bj][m][n], 0, 0, 0); __builtin_amdgcn_s_setprio(0); } while (0)
; #define PG8_WAIT_V(n) asm volatile("s_waitcnt vmcnt(" #n ")" ::: "memory")
; #define PG8_WAIT_L(n) asm volatile("s_waitcnt lgkmcnt(" #n ")" ::: "memory")
; #define PG8_BAR __builtin_amdgcn_s_barrier()
; #define PG8_SCHED __builtin_amdgcn_sched_barrier(0)
; template <class Epi, class Sched, bool ALIGN_EPI = false, bool SP2 = false>
; __device__ __forceinline__ void gemm_phase(PG8_LAS unsigned char* lds, const Gemm g, const Sched& S, const Epi& E) {
;     ...
;             PG8_LDA(At, 1, 1); PG8_STAGE(PG8_SB(1, 0), b3, voffB); PG8_STAGE(PG8_SB(1, 1), b3 + hstep, voffB); PG8_STAGE(PG8_SA(1, 0), a3, voffA);
;             PG8_WAIT_V(8); PG8_WAIT_L(0); PG8_BAR; PG8_MMA(1, 0, At, B0); PG8_MMA(1, 1, At, B1); PG8_BAR; PG8_SCHED;
	s_add_i32 s18, s44, s23
	v_lshl_add_u64 v[144:145], v[144:145], 0, s[34:35]
	s_mov_b32 m0, s18
	ds_read_b128 v[198:201], v148 offset:49152
	ds_read_b128 v[202:205], v148 offset:50176
	ds_read_b128 v[220:223], v148 offset:51200
	ds_read_b128 v[224:227], v148 offset:52224
	ds_read_b128 v[228:231], v148 offset:53248
	ds_read_b128 v[232:235], v148 offset:54272
	ds_read_b128 v[236:239], v148 offset:55296
	ds_read_b128 v[240:243], v148 offset:56320
	global_load_lds_dwordx4 v[144:145], off
	s_add_i32 m0, s18, 0x2000
	s_add_u32 s16, s16, 0x80080
	v_lshl_add_u64 v[144:145], v[184:185], 0, s[34:35]
	s_addc_u32 s17, s17, 0
	s_add_i32 s18, s45, s23
	global_load_lds_dwordx4 v[144:145], off
	v_lshl_add_u64 v[144:145], s[16:17], 0, v[2:3]
	s_mov_b32 m0, s18
	s_nop 0
	global_load_lds_dwordx4 v[144:145], off
	v_lshl_add_u64 v[144:145], s[16:17], 0, v[132:133]
	s_add_i32 m0, s18, 0x2000
	s_nop 0
	global_load_lds_dwordx4 v[144:145], off
	v_lshl_add_u64 v[144:145], v[186:187], 0, s[34:35]
	s_mov_b32 m0, s28
	s_nop 0
	global_load_lds_dwordx4 v[144:145], off
	v_lshl_add_u64 v[144:145], v[196:197], 0, s[34:35]
	s_mov_b32 m0, s29
	s_nop 0
	global_load_lds_dwordx4 v[144:145], off
	s_waitcnt vmcnt(8)
	s_waitcnt lgkmcnt(0)
	s_barrier
	s_setprio 1
	s_waitcnt lgkmcnt(0)
	v_mfma_f32_16x16x32_bf16 v[64:67], v[150:153], v[198:201], v[64:67]
	v_mfma_f32_16x16x32_bf16 v[64:67], v[154:157], v[202:205], v[64:67]
	v_mfma_f32_16x16x32_bf16 v[56:59], v[150:153], v[220:223], v[56:59]
	v_mfma_f32_16x16x32_bf16 v[56:59], v[154:157], v[224:227], v[56:59]
	v_mfma_f32_16x16x32_bf16 v[40:43], v[150:153], v[228:231], v[40:43]
	v_mfma_f32_16x16x32_bf16 v[40:43], v[154:157], v[232:235], v[40:43]
	v_mfma_f32_16x16x32_bf16 v[24:27], v[150:153], v[236:239], v[24:27]
	v_mfma_f32_16x16x32_bf16 v[24:27], v[154:157], v[240:243], v[24:27]
	v_mfma_f32_16x16x32_bf16 v[60:63], v[158:161], v[198:201], v[60:63]
	v_mfma_f32_16x16x32_bf16 v[60:63], v[162:165], v[202:205], v[60:63]
	v_mfma_f32_16x16x32_bf16 v[48:51], v[158:161], v[220:223], v[48:51]
	v_mfma_f32_16x16x32_bf16 v[48:51], v[162:165], v[224:227], v[48:51]
	v_mfma_f32_16x16x32_bf16 v[32:35], v[158:161], v[228:231], v[32:35]
	v_mfma_f32_16x16x32_bf16 v[32:35], v[162:165], v[232:235], v[32:35]
	v_mfma_f32_16x16x32_bf16 v[16:19], v[158:161], v[236:239], v[16:19]
	v_mfma_f32_16x16x32_bf16 v[16:19], v[162:165], v[240:243], v[16:19]
	s_setprio 0
	s_setprio 1
	v_mfma_f32_16x16x32_bf16 v[52:55], v[166:169], v[198:201], v[52:55]
	v_mfma_f32_16x16x32_bf16 v[52:55], v[170:173], v[202:205], v[52:55]
	v_mfma_f32_16x16x32_bf16 v[36:39], v[166:169], v[220:223], v[36:39]
	v_mfma_f32_16x16x32_bf16 v[36:39], v[170:173], v[224:227], v[36:39]
	v_mfma_f32_16x16x32_bf16 v[20:23], v[166:169], v[228:231], v[20:23]
	v_mfma_f32_16x16x32_bf16 v[20:23], v[170:173], v[232:235], v[20:23]
	v_mfma_f32_16x16x32_bf16 v[8:11], v[166:169], v[236:239], v[8:11]
	v_mfma_f32_16x16x32_bf16 v[8:11], v[170:173], v[240:243], v[8:11]
	v_mfma_f32_16x16x32_bf16 v[44:47], v[174:177], v[198:201], v[44:47]
	v_mfma_f32_16x16x32_bf16 v[44:47], v[178:181], v[202:205], v[44:47]
	v_mfma_f32_16x16x32_bf16 v[28:31], v[174:177], v[220:223], v[28:31]
	v_mfma_f32_16x16x32_bf16 v[28:31], v[178:181], v[224:227], v[28:31]
	v_mfma_f32_16x16x32_bf16 v[12:15], v[174:177], v[228:231], v[12:15]
	v_mfma_f32_16x16x32_bf16 v[12:15], v[178:181], v[232:235], v[12:15]
	v_mfma_f32_16x16x32_bf16 v[4:7], v[174:177], v[236:239], v[4:7]
	v_mfma_f32_16x16x32_bf16 v[4:7], v[178:181], v[240:243], v[4:7]
	s_setprio 0
	s_barrier
	s_add_i32 s43, s43, 2
	s_add_u32 s14, s14, 0x100
	s_addc_u32 s15, s15, 0
	s_add_u32 s41, s41, 0x100
	s_addc_u32 s42, s42, 0
	s_cmp_gt_u32 s43, 29
	s_cbranch_scc0 .LBB11_913
	s_and_b64 vcc, exec, s[4:5]
	s_cbranch_vccz .LBB11_916
	s_barrier

; #define PG8_STAGE(bufoff, gbase, voff) do { _Pragma("unroll") for (int _i = 0; _i < 2; ++_i) \
;         __builtin_amdgcn_global_load_lds((const unsigned*)((const char*)(gbase) + (voff)[_i]), (PG8_LAS unsigned*)(lds + (bufoff) + ldsw + _i * 8192), 16, 0, 0); } while (0)
; #define PG8_LDA(dst, b, h) do { _Pragma("unroll") for (int m = 0; m < 4; ++m) _Pragma("unroll") for (int k = 0; k < 2; ++k) dst[m][k] = *(const PG8_LAS bf16x8*)(lds + PG8_SA(b, h) + aoff + m * 2048 + k * 1024); } while (0)
; #define PG8_LDB(dst, b, h) do { _Pragma("unroll") for (int n = 0; n < 2; ++n) _Pragma("unroll") for (int k = 0; k < 2; ++k) dst[n][k] = *(const PG8_LAS bf16x8*)(lds + PG8_SB(b, h) + boff + n * 2048 + k * 1024); } while (0)
; #define PG8_MMA(ai, bj, At, Bt) do { __builtin_amdgcn_s_setprio(1); _Pragma("unroll") for (int m = 0; m < 4; ++m) _Pragma("unroll") for (int n = 0; n < 2; ++n) _Pragma("unroll") for (int k = 0; k < 2; ++k) \
;         acc[ai][bj][m][n] = __builtin_amdgcn_mfma_f32_16x16x32_bf16(Bt[n][k], At[m][k], acc[ai][bj][m][n], 0, 0, 0); __builtin_amdgcn_s_setprio(0); } while (0)
; #define PG8_WAIT_V(n) asm volatile("s_waitcnt vmcnt(" #n ")" ::: "memory")
; #define PG8_WAIT_L(n) asm volatile("s_waitcnt lgkmcnt(" #n ")" ::: "memory")
; #define PG8_BAR __builtin_amdgcn_s_barrier()
; #define PG8_SCHED __builtin_amdgcn_sched_barrier(0)
; template <class Epi, class Sched, bool ALIGN_EPI = false, bool SP2 = false>
; __device__ __forceinline__ void gemm_phase(PG8_LAS unsigned char* lds, const Gemm g, const Sched& S, const Epi& E) {
;     ...
;             const char* a2 = last ? nA : cA + (size_t)(t + 2) * kstep; const char* b2 = last ? nB : cB + (size_t)(t + 2) * kstep;
;             const char* a3 = a2 + kstep; const char* b3 = b2 + kstep;
;             if (last && has_next) S.a_ready(nxt);
;             if constexpr (SP2) {
;             PG8_LDB(B0, 0, 0); PG8_LDB(B1, 0, 1); PG8_SCHED; PG8_LDA(At, 0, 0); PG8_STAGE(PG8_SA(1, 1), a1 + hstep, voffA);
;             PG8_WAIT_V(8); PG8_WAIT_L(0); PG8_BAR; PG8_MMA(0, 0, At, B0); PG8_MMA(0, 1, At, B1); PG8_BAR; PG8_SCHED;
;             PG8_LDA(At, 0, 1); PG8_STAGE(PG8_SB(0, 0), b2, voffB); PG8_STAGE(PG8_SB(0, 1), b2 + hstep, voffB); PG8_STAGE(PG8_SA(0, 0), a2, voffA);
;             PG8_WAIT_V(8); PG8_WAIT_L(0); PG8_BAR; PG8_MMA(1, 0, At, B0); PG8_MMA(1, 1, At, B1); PG8_BAR; PG8_SCHED;
.LBB11_1071:
	s_add_u32 s16, s14, 0xfff80080
	s_addc_u32 s17, s15, -1
	s_add_i32 s46, 0, 0x10000
	s_cmp_eq_u32 s45, 28
	s_cselect_b32 s19, s9, s17
	s_cselect_b32 s18, s41, s16
	v_add_u32_e32 v2, s46, v168
	s_cselect_b32 s17, s7, s44
	s_cselect_b32 s16, s42, s43
	s_add_i32 s48, 0, 0x14000
	ds_read_b128 v[132:135], v2
	ds_read_b128 v[136:139], v2 offset:1024
	ds_read_b128 v[140:143], v2 offset:2048
	ds_read_b128 v[144:147], v2 offset:3072
	v_add_u32_e32 v2, s48, v168
	ds_read_b128 v[170:173], v2
	ds_read_b128 v[174:177], v2 offset:1024
	ds_read_b128 v[178:181], v2 offset:2048
	ds_read_b128 v[198:201], v2 offset:3072
	v_lshl_add_u64 v[166:167], s[14:15], 0, v[162:163]
	s_add_i32 m0, s25, 0xc000
	ds_read_b128 v[202:205], v169
	ds_read_b128 v[220:223], v169 offset:1024
	ds_read_b128 v[224:227], v169 offset:2048
	ds_read_b128 v[228:231], v169 offset:3072
	ds_read_b128 v[232:235], v169 offset:4096
	ds_read_b128 v[236:239], v169 offset:5120
	ds_read_b128 v[240:243], v169 offset:6144
	ds_read_b128 v[244:247], v169 offset:7168
	global_load_lds_dwordx4 v[166:167], off
	v_lshl_add_u64 v[166:167], s[14:15], 0, v[164:165]
	s_add_i32 m0, s25, 0xe000
	s_nop 0
	global_load_lds_dwordx4 v[166:167], off
	s_waitcnt vmcnt(8)
	s_waitcnt lgkmcnt(0)
	s_barrier
	s_setprio 1
	s_waitcnt lgkmcnt(0)
	v_mfma_f32_16x16x32_bf16 v[128:131], v[132:135], v[202:205], v[128:131]
	v_mfma_f32_16x16x32_bf16 v[128:131], v[136:139], v[220:223], v[128:131]
	v_mfma_f32_16x16x32_bf16 v[120:123], v[132:135], v[224:227], v[120:123]
	v_mfma_f32_16x16x32_bf16 v[120:123], v[136:139], v[228:231], v[120:123]
	v_mfma_f32_16x16x32_bf16 v[104:107], v[132:135], v[232:235], v[104:107]
	v_mfma_f32_16x16x32_bf16 v[104:107], v[136:139], v[236:239], v[104:107]
	v_mfma_f32_16x16x32_bf16 v[88:91], v[132:135], v[240:243], v[88:91]
	v_mfma_f32_16x16x32_bf16 v[88:91], v[136:139], v[244:247], v[88:91]
	v_mfma_f32_16x16x32_bf16 v[124:127], v[140:143], v[202:205], v[124:127]
	v_mfma_f32_16x16x32_bf16 v[124:127], v[144:147], v[220:223], v[124:127]
	v_mfma_f32_16x16x32_bf16 v[112:115], v[140:143], v[224:227], v[112:115]
	v_mfma_f32_16x16x32_bf16 v[112:115], v[144:147], v[228:231], v[112:115]
	v_mfma_f32_16x16x32_bf16 v[96:99], v[140:143], v[232:235], v[96:99]
	v_mfma_f32_16x16x32_bf16 v[96:99], v[144:147], v[236:239], v[96:99]
	v_mfma_f32_16x16x32_bf16 v[80:83], v[140:143], v[240:243], v[80:83]
	v_mfma_f32_16x16x32_bf16 v[80:83], v[144:147], v[244:247], v[80:83]
	s_setprio 0
	s_setprio 1
	v_mfma_f32_16x16x32_bf16 v[116:119], v[170:173], v[202:205], v[116:119]
	v_mfma_f32_16x16x32_bf16 v[116:119], v[174:177], v[220:223], v[116:119]
	v_mfma_f32_16x16x32_bf16 v[100:103], v[170:173], v[224:227], v[100:103]
	v_mfma_f32_16x16x32_bf16 v[100:103], v[174:177], v[228:231], v[100:103]
	v_mfma_f32_16x16x32_bf16 v[84:87], v[170:173], v[232:235], v[84:87]
	v_mfma_f32_16x16x32_bf16 v[84:87], v[174:177], v[236:239], v[84:87]
	v_mfma_f32_16x16x32_bf16 v[72:75], v[170:173], v[240:243], v[72:75]
	v_mfma_f32_16x16x32_bf16 v[72:75], v[174:177], v[244:247], v[72:75]
	v_mfma_f32_16x16x32_bf16 v[108:111], v[178:181], v[202:205], v[108:111]
	v_mfma_f32_16x16x32_bf16 v[108:111], v[198:201], v[220:223], v[108:111]
	v_mfma_f32_16x16x32_bf16 v[92:95], v[178:181], v[224:227], v[92:95]
	v_mfma_f32_16x16x32_bf16 v[92:95], v[198:201], v[228:231], v[92:95]
	v_mfma_f32_16x16x32_bf16 v[76:79], v[178:181], v[232:235], v[76:79]
	v_mfma_f32_16x16x32_bf16 v[76:79], v[198:201], v[236:239], v[76:79]
	v_mfma_f32_16x16x32_bf16 v[68:71], v[178:181], v[240:243], v[68:71]
	v_mfma_f32_16x16x32_bf16 v[68:71], v[198:201], v[244:247], v[68:71]
	s_setprio 0
	s_barrier
	s_add_i32 s46, s46, s24
	v_lshl_add_u64 v[166:167], s[16:17], 0, v[154:155]
	s_mov_b32 m0, s46
	ds_read_b128 v[202:205], v169 offset:16384
	ds_read_b128 v[220:223], v169 offset:17408
	ds_read_b128 v[224:227], v169 offset:18432
	ds_read_b128 v[228:231], v169 offset:19456
	ds_read_b128 v[232:235], v169 offset:20480
	ds_read_b128 v[236:239], v169 offset:21504
	ds_read_b128 v[240:243], v169 offset:22528
	ds_read_b128 v[244:247], v169 offset:23552
	global_load_lds_dwordx4 v[166:167], off
	s_add_i32 m0, s46, 0x2000
	s_add_u32 s46, s16, 0x80000
	v_lshl_add_u64 v[196:197], s[16:17], 0, v[150:151]
	s_addc_u32 s47, s17, 0
	s_add_i32 s48, s48, s24
	global_load_lds_dwordx4 v[196:197], off
	v_lshl_add_u64 v[206:207], s[46:47], 0, v[154:155]
	s_mov_b32 m0, s48
	v_lshl_add_u64 v[184:185], s[18:19], 0, v[152:153]
	global_load_lds_dwordx4 v[206:207], off
	v_lshl_add_u64 v[206:207], s[46:47], 0, v[150:151]
	s_add_i32 m0, s48, 0x2000
	s_nop 0
	global_load_lds_dwordx4 v[206:207], off
	v_lshl_add_u64 v[206:207], s[18:19], 0, v[156:157]
	s_mov_b32 m0, s25
	s_nop 0
	global_load_lds_dwordx4 v[206:207], off
	s_mov_b32 m0, s26
	s_nop 0
	global_load_lds_dwordx4 v[184:185], off
	s_waitcnt vmcnt(8)
	s_waitcnt lgkmcnt(0)
	s_barrier
; #define PG8_STAGE(bufoff, gbase, voff) do { _Pragma("unroll") for (int _i = 0; _i < 2; ++_i) \
;         __builtin_amdgcn_global_load_lds((const unsigned*)((const char*)(gbase) + (voff)[_i]), (PG8_LAS unsigned*)(lds + (bufoff) + ldsw + _i * 8192), 16, 0, 0); } while (0)
; #define PG8_LDA(dst, b, h) do { _Pragma("unroll") for (int m = 0; m < 4; ++m) _Pragma("unroll") for (int k = 0; k < 2; ++k) dst[m][k] = *(const PG8_LAS bf16x8*)(lds + PG8_SA(b, h) + aoff + m * 2048 + k * 1024); } while (0)
; #define PG8_LDB(dst, b, h) do { _Pragma("unroll") for (int n = 0; n < 2; ++n) _Pragma("unroll") for (int k = 0; k < 2; ++k) dst[n][k] = *(const PG8_LAS bf16x8*)(lds + PG8_SB(b, h) + boff + n * 2048 + k * 1024); } while (0)
; #define PG8_MMA(ai, bj, At, Bt) do { __builtin_amdgcn_s_setprio(1); _Pragma("unroll") for (int m = 0; m < 4; ++m) _Pragma("unroll") for (int n = 0; n < 2; ++n) _Pragma("unroll") for (int k = 0; k < 2; ++k) \
;         acc[ai][bj][m][n] = __builtin_amdgcn_mfma_f32_16x16x32_bf16(Bt[n][k], At[m][k], acc[ai][bj][m][n], 0, 0, 0); __builtin_amdgcn_s_setprio(0); } while (0)
; #define PG8_WAIT_V(n) asm volatile("s_waitcnt vmcnt(" #n ")" ::: "memory")
; #define PG8_WAIT_L(n) asm volatile("s_waitcnt lgkmcnt(" #n ")" ::: "memory")
; #define PG8_BAR __builtin_amdgcn_s_barrier()
; #define PG8_SCHED __builtin_amdgcn_sched_barrier(0)
; template <class Epi, class Sched, bool ALIGN_EPI = false, bool SP2 = false>
; __device__ __forceinline__ void gemm_phase(PG8_LAS unsigned char* lds, const Gemm g, const Sched& S, const Epi& E) {
;     ...
;             PG8_WAIT_V(8); PG8_WAIT_L(0); PG8_BAR; PG8_MMA(1, 0, At, B0); PG8_MMA(1, 1, At, B1); PG8_BAR; PG8_SCHED;
;             PG8_LDB(B0, 1, 0); PG8_LDB(B1, 1, 1); PG8_SCHED; PG8_LDA(At, 1, 0); PG8_STAGE(PG8_SA(0, 1), a2 + hstep, voffA);
;             PG8_WAIT_V(8); PG8_WAIT_L(0); PG8_BAR; PG8_MMA(0, 0, At, B0); PG8_MMA(0, 1, At, B1); PG8_BAR; PG8_SCHED;
	s_setprio 1
	s_waitcnt lgkmcnt(0)
	v_mfma_f32_16x16x32_bf16 v[64:67], v[132:135], v[202:205], v[64:67]
	v_mfma_f32_16x16x32_bf16 v[64:67], v[136:139], v[220:223], v[64:67]
	v_mfma_f32_16x16x32_bf16 v[56:59], v[132:135], v[224:227], v[56:59]
	v_mfma_f32_16x16x32_bf16 v[56:59], v[136:139], v[228:231], v[56:59]
	v_mfma_f32_16x16x32_bf16 v[40:43], v[132:135], v[232:235], v[40:43]
	v_mfma_f32_16x16x32_bf16 v[40:43], v[136:139], v[236:239], v[40:43]
	v_mfma_f32_16x16x32_bf16 v[24:27], v[132:135], v[240:243], v[24:27]
	v_mfma_f32_16x16x32_bf16 v[24:27], v[136:139], v[244:247], v[24:27]
	v_mfma_f32_16x16x32_bf16 v[60:63], v[140:143], v[202:205], v[60:63]
	v_mfma_f32_16x16x32_bf16 v[60:63], v[144:147], v[220:223], v[60:63]
	v_mfma_f32_16x16x32_bf16 v[48:51], v[140:143], v[224:227], v[48:51]
	v_mfma_f32_16x16x32_bf16 v[48:51], v[144:147], v[228:231], v[48:51]
	v_mfma_f32_16x16x32_bf16 v[32:35], v[140:143], v[232:235], v[32:35]
	v_mfma_f32_16x16x32_bf16 v[32:35], v[144:147], v[236:239], v[32:35]
	v_mfma_f32_16x16x32_bf16 v[16:19], v[140:143], v[240:243], v[16:19]
	v_mfma_f32_16x16x32_bf16 v[16:19], v[144:147], v[244:247], v[16:19]
	s_setprio 0
	s_setprio 1
	v_mfma_f32_16x16x32_bf16 v[52:55], v[170:173], v[202:205], v[52:55]
	v_mfma_f32_16x16x32_bf16 v[52:55], v[174:177], v[220:223], v[52:55]
	v_mfma_f32_16x16x32_bf16 v[36:39], v[170:173], v[224:227], v[36:39]
	v_mfma_f32_16x16x32_bf16 v[36:39], v[174:177], v[228:231], v[36:39]
	v_mfma_f32_16x16x32_bf16 v[20:23], v[170:173], v[232:235], v[20:23]
	v_mfma_f32_16x16x32_bf16 v[20:23], v[174:177], v[236:239], v[20:23]
	v_mfma_f32_16x16x32_bf16 v[8:11], v[170:173], v[240:243], v[8:11]
	v_mfma_f32_16x16x32_bf16 v[8:11], v[174:177], v[244:247], v[8:11]
	v_mfma_f32_16x16x32_bf16 v[44:47], v[178:181], v[202:205], v[44:47]
	v_mfma_f32_16x16x32_bf16 v[44:47], v[198:201], v[220:223], v[44:47]
	v_mfma_f32_16x16x32_bf16 v[28:31], v[178:181], v[224:227], v[28:31]
	v_mfma_f32_16x16x32_bf16 v[28:31], v[198:201], v[228:231], v[28:31]
	v_mfma_f32_16x16x32_bf16 v[12:15], v[178:181], v[232:235], v[12:15]
	v_mfma_f32_16x16x32_bf16 v[12:15], v[198:201], v[236:239], v[12:15]
	v_mfma_f32_16x16x32_bf16 v[4:7], v[178:181], v[240:243], v[4:7]
	v_mfma_f32_16x16x32_bf16 v[4:7], v[198:201], v[244:247], v[4:7]
	s_setprio 0
	s_barrier
	s_add_i32 s46, 0, 0x18000
	v_add_u32_e32 v2, s46, v168
	s_add_i32 s47, 0, 0x1c000
	ds_read_b128 v[132:135], v2
	ds_read_b128 v[136:139], v2 offset:1024
	ds_read_b128 v[140:143], v2 offset:2048
	ds_read_b128 v[144:147], v2 offset:3072
	v_add_u32_e32 v2, s47, v168
	ds_read_b128 v[170:173], v2
	ds_read_b128 v[174:177], v2 offset:1024
	ds_read_b128 v[178:181], v2 offset:2048
	ds_read_b128 v[198:201], v2 offset:3072
	s_add_u32 s18, s18, 0x80000
	s_addc_u32 s19, s19, 0
	s_mov_b32 m0, s27
	v_lshl_add_u64 v[186:187], s[18:19], 0, v[156:157]
	ds_read_b128 v[202:205], v169 offset:32768
	ds_read_b128 v[220:223], v169 offset:33792
	ds_read_b128 v[224:227], v169 offset:34816
	ds_read_b128 v[228:231], v169 offset:35840
	ds_read_b128 v[232:235], v169 offset:36864
	ds_read_b128 v[236:239], v169 offset:37888
	ds_read_b128 v[240:243], v169 offset:38912
	ds_read_b128 v[244:247], v169 offset:39936
	global_load_lds_dwordx4 v[186:187], off
	v_lshl_add_u64 v[186:187], s[18:19], 0, v[152:153]
	s_mov_b32 m0, s28
	s_nop 0
	global_load_lds_dwordx4 v[186:187], off
	s_waitcnt vmcnt(8)
	s_waitcnt lgkmcnt(0)
	s_barrier
	s_setprio 1
	s_waitcnt lgkmcnt(0)
	v_mfma_f32_16x16x32_bf16 v[128:131], v[132:135], v[202:205], v[128:131]
	v_mfma_f32_16x16x32_bf16 v[128:131], v[136:139], v[220:223], v[128:131]
	v_mfma_f32_16x16x32_bf16 v[120:123], v[132:135], v[224:227], v[120:123]
	v_mfma_f32_16x16x32_bf16 v[120:123], v[136:139], v[228:231], v[120:123]
	v_mfma_f32_16x16x32_bf16 v[104:107], v[132:135], v[232:235], v[104:107]
	v_mfma_f32_16x16x32_bf16 v[104:107], v[136:139], v[236:239], v[104:107]
	v_mfma_f32_16x16x32_bf16 v[88:91], v[132:135], v[240:243], v[88:91]
	v_mfma_f32_16x16x32_bf16 v[88:91], v[136:139], v[244:247], v[88:91]
	v_mfma_f32_16x16x32_bf16 v[124:127], v[140:143], v[202:205], v[124:127]
	v_mfma_f32_16x16x32_bf16 v[124:127], v[144:147], v[220:223], v[124:127]
	v_mfma_f32_16x16x32_bf16 v[112:115], v[140:143], v[224:227], v[112:115]
	v_mfma_f32_16x16x32_bf16 v[112:115], v[144:147], v[228:231], v[112:115]
	v_mfma_f32_16x16x32_bf16 v[96:99], v[140:143], v[232:235], v[96:99]
	v_mfma_f32_16x16x32_bf16 v[96:99], v[144:147], v[236:239], v[96:99]
	v_mfma_f32_16x16x32_bf16 v[80:83], v[140:143], v[240:243], v[80:83]
	v_mfma_f32_16x16x32_bf16 v[80:83], v[144:147], v[244:247], v[80:83]
	s_setprio 0
	s_setprio 1
	v_mfma_f32_16x16x32_bf16 v[116:119], v[170:173], v[202:205], v[116:119]
	v_mfma_f32_16x16x32_bf16 v[116:119], v[174:177], v[220:223], v[116:119]
	v_mfma_f32_16x16x32_bf16 v[100:103], v[170:173], v[224:227], v[100:103]
	v_mfma_f32_16x16x32_bf16 v[100:103], v[174:177], v[228:231], v[100:103]
	v_mfma_f32_16x16x32_bf16 v[84:87], v[170:173], v[232:235], v[84:87]
	v_mfma_f32_16x16x32_bf16 v[84:87], v[174:177], v[236:239], v[84:87]
	v_mfma_f32_16x16x32_bf16 v[72:75], v[170:173], v[240:243], v[72:75]
	v_mfma_f32_16x16x32_bf16 v[72:75], v[174:177], v[244:247], v[72:75]
	v_mfma_f32_16x16x32_bf16 v[108:111], v[178:181], v[202:205], v[108:111]
	v_mfma_f32_16x16x32_bf16 v[108:111], v[198:201], v[220:223], v[108:111]
	v_mfma_f32_16x16x32_bf16 v[92:95], v[178:181], v[224:227], v[92:95]
	v_mfma_f32_16x16x32_bf16 v[92:95], v[198:201], v[228:231], v[92:95]
	v_mfma_f32_16x16x32_bf16 v[76:79], v[178:181], v[232:235], v[76:79]
	v_mfma_f32_16x16x32_bf16 v[76:79], v[198:201], v[236:239], v[76:79]
	v_mfma_f32_16x16x32_bf16 v[68:71], v[178:181], v[240:243], v[68:71]
	v_mfma_f32_16x16x32_bf16 v[68:71], v[198:201], v[244:247], v[68:71]
	s_setprio 0
	s_barrier
; #define PG8_STAGE(bufoff, gbase, voff) do { _Pragma("unroll") for (int _i = 0; _i < 2; ++_i) \
;         __builtin_amdgcn_global_load_lds((const unsigned*)((const char*)(gbase) + (voff)[_i]), (PG8_LAS unsigned*)(lds + (bufoff) + ldsw + _i * 8192), 16, 0, 0); } while (0)
; #define PG8_LDA(dst, b, h) do { _Pragma("unroll") for (int m = 0; m < 4; ++m) _Pragma("unroll") for (int k = 0; k < 2; ++k) dst[m][k] = *(const PG8_LAS bf16x8*)(lds + PG8_SA(b, h) + aoff + m * 2048 + k * 1024); } while (0)
; #define PG8_MMA(ai, bj, At, Bt) do { __builtin_amdgcn_s_setprio(1); _Pragma("unroll") for (int m = 0; m < 4; ++m) _Pragma("unroll") for (int n = 0; n < 2; ++n) _Pragma("unroll") for (int k = 0; k < 2; ++k) \
;         acc[ai][bj][m][n] = __builtin_amdgcn_mfma_f32_16x16x32_bf16(Bt[n][k], At[m][k], acc[ai][bj][m][n], 0, 0, 0); __builtin_amdgcn_s_setprio(0); } while (0)
; #define PG8_WAIT_V(n) asm volatile("s_waitcnt vmcnt(" #n ")" ::: "memory")
; #define PG8_WAIT_L(n) asm volatile("s_waitcnt lgkmcnt(" #n ")" ::: "memory")
; #define PG8_BAR __builtin_amdgcn_s_barrier()
; #define PG8_SCHED __builtin_amdgcn_sched_barrier(0)
; template <class Epi, class Sched, bool ALIGN_EPI = false, bool SP2 = false>
; __device__ __forceinline__ void gemm_phase(PG8_LAS unsigned char* lds, const Gemm g, const Sched& S, const Epi& E) {
;     ...
;             PG8_LDA(At, 1, 1); PG8_STAGE(PG8_SB(1, 0), b3, voffB); PG8_STAGE(PG8_SB(1, 1), b3 + hstep, voffB); PG8_STAGE(PG8_SA(1, 0), a3, voffA);
;             PG8_WAIT_V(8); PG8_WAIT_L(0); PG8_BAR; PG8_MMA(1, 0, At, B0); PG8_MMA(1, 1, At, B1); PG8_BAR; PG8_SCHED;
	s_add_i32 s18, s46, s24
	v_lshl_add_u64 v[166:167], v[166:167], 0, s[34:35]
	s_mov_b32 m0, s18
	ds_read_b128 v[202:205], v169 offset:49152
	ds_read_b128 v[220:223], v169 offset:50176
	ds_read_b128 v[224:227], v169 offset:51200
	ds_read_b128 v[228:231], v169 offset:52224
	ds_read_b128 v[232:235], v169 offset:53248
	ds_read_b128 v[236:239], v169 offset:54272
	ds_read_b128 v[240:243], v169 offset:55296
	ds_read_b128 v[244:247], v169 offset:56320
	global_load_lds_dwordx4 v[166:167], off
	s_add_i32 m0, s18, 0x2000
	s_add_u32 s16, s16, 0x80080
	v_lshl_add_u64 v[166:167], v[196:197], 0, s[34:35]
	s_addc_u32 s17, s17, 0
	s_add_i32 s18, s47, s24
	global_load_lds_dwordx4 v[166:167], off
	v_lshl_add_u64 v[166:167], s[16:17], 0, v[154:155]
	s_mov_b32 m0, s18
	s_nop 0
	global_load_lds_dwordx4 v[166:167], off
	v_lshl_add_u64 v[166:167], s[16:17], 0, v[150:151]
	s_add_i32 m0, s18, 0x2000
	s_nop 0
	global_load_lds_dwordx4 v[166:167], off
	v_lshl_add_u64 v[166:167], v[206:207], 0, s[34:35]
	s_mov_b32 m0, s33
	s_nop 0
	global_load_lds_dwordx4 v[166:167], off
	v_lshl_add_u64 v[166:167], v[184:185], 0, s[34:35]
	s_mov_b32 m0, s38
	s_nop 0
	global_load_lds_dwordx4 v[166:167], off
	s_waitcnt vmcnt(8)
	s_waitcnt lgkmcnt(0)
	s_barrier
	s_setprio 1
	s_waitcnt lgkmcnt(0)
	v_mfma_f32_16x16x32_bf16 v[64:67], v[132:135], v[202:205], v[64:67]
	v_mfma_f32_16x16x32_bf16 v[64:67], v[136:139], v[220:223], v[64:67]
	v_mfma_f32_16x16x32_bf16 v[56:59], v[132:135], v[224:227], v[56:59]
	v_mfma_f32_16x16x32_bf16 v[56:59], v[136:139], v[228:231], v[56:59]
	v_mfma_f32_16x16x32_bf16 v[40:43], v[132:135], v[232:235], v[40:43]
	v_mfma_f32_16x16x32_bf16 v[40:43], v[136:139], v[236:239], v[40:43]
	v_mfma_f32_16x16x32_bf16 v[24:27], v[132:135], v[240:243], v[24:27]
	v_mfma_f32_16x16x32_bf16 v[24:27], v[136:139], v[244:247], v[24:27]
	v_mfma_f32_16x16x32_bf16 v[60:63], v[140:143], v[202:205], v[60:63]
	v_mfma_f32_16x16x32_bf16 v[60:63], v[144:147], v[220:223], v[60:63]
	v_mfma_f32_16x16x32_bf16 v[48:51], v[140:143], v[224:227], v[48:51]
	v_mfma_f32_16x16x32_bf16 v[48:51], v[144:147], v[228:231], v[48:51]
	v_mfma_f32_16x16x32_bf16 v[32:35], v[140:143], v[232:235], v[32:35]
	v_mfma_f32_16x16x32_bf16 v[32:35], v[144:147], v[236:239], v[32:35]
	v_mfma_f32_16x16x32_bf16 v[16:19], v[140:143], v[240:243], v[16:19]
	v_mfma_f32_16x16x32_bf16 v[16:19], v[144:147], v[244:247], v[16:19]
	s_setprio 0
	s_setprio 1
	v_mfma_f32_16x16x32_bf16 v[52:55], v[170:173], v[202:205], v[52:55]
	v_mfma_f32_16x16x32_bf16 v[52:55], v[174:177], v[220:223], v[52:55]
	v_mfma_f32_16x16x32_bf16 v[36:39], v[170:173], v[224:227], v[36:39]
	v_mfma_f32_16x16x32_bf16 v[36:39], v[174:177], v[228:231], v[36:39]
	v_mfma_f32_16x16x32_bf16 v[20:23], v[170:173], v[232:235], v[20:23]
	v_mfma_f32_16x16x32_bf16 v[20:23], v[174:177], v[236:239], v[20:23]
	v_mfma_f32_16x16x32_bf16 v[8:11], v[170:173], v[240:243], v[8:11]
	v_mfma_f32_16x16x32_bf16 v[8:11], v[174:177], v[244:247], v[8:11]
	v_mfma_f32_16x16x32_bf16 v[44:47], v[178:181], v[202:205], v[44:47]
	v_mfma_f32_16x16x32_bf16 v[44:47], v[198:201], v[220:223], v[44:47]
	v_mfma_f32_16x16x32_bf16 v[28:31], v[178:181], v[224:227], v[28:31]
	v_mfma_f32_16x16x32_bf16 v[28:31], v[198:201], v[228:231], v[28:31]
	v_mfma_f32_16x16x32_bf16 v[12:15], v[178:181], v[232:235], v[12:15]
	v_mfma_f32_16x16x32_bf16 v[12:15], v[198:201], v[236:239], v[12:15]
	v_mfma_f32_16x16x32_bf16 v[4:7], v[178:181], v[240:243], v[4:7]
	v_mfma_f32_16x16x32_bf16 v[4:7], v[198:201], v[244:247], v[4:7]
	s_setprio 0
	s_barrier
	s_add_i32 s45, s45, 2
	s_add_u32 s14, s14, 0x100
	s_addc_u32 s15, s15, 0
	s_add_u32 s43, s43, 0x100
	s_addc_u32 s44, s44, 0
	s_cmp_gt_u32 s45, 29
	s_cbranch_scc0 .LBB11_1071
	s_and_b64 vcc, exec, s[4:5]
	s_cbranch_vccz .LBB11_1074
	s_barrier

; #define PG8_STAGE(bufoff, gbase, voff) do { _Pragma("unroll") for (int _i = 0; _i < 2; ++_i) \
;         __builtin_amdgcn_global_load_lds((const unsigned*)((const char*)(gbase) + (voff)[_i]), (PG8_LAS unsigned*)(lds + (bufoff) + ldsw + _i * 8192), 16, 0, 0); } while (0)
; #define PG8_LDA(dst, b, h) do { _Pragma("unroll") for (int m = 0; m < 4; ++m) _Pragma("unroll") for (int k = 0; k < 2; ++k) dst[m][k] = *(const PG8_LAS bf16x8*)(lds + PG8_SA(b, h) + aoff + m * 2048 + k * 1024); } while (0)
; #define PG8_LDB(dst, b, h) do { _Pragma("unroll") for (int n = 0; n < 2; ++n) _Pragma("unroll") for (int k = 0; k < 2; ++k) dst[n][k] = *(const PG8_LAS bf16x8*)(lds + PG8_SB(b, h) + boff + n * 2048 + k * 1024); } while (0)
; #define PG8_MMA(ai, bj, At, Bt) do { __builtin_amdgcn_s_setprio(1); _Pragma("unroll") for (int m = 0; m < 4; ++m) _Pragma("unroll") for (int n = 0; n < 2; ++n) _Pragma("unroll") for (int k = 0; k < 2; ++k) \
;         acc[ai][bj][m][n] = __builtin_amdgcn_mfma_f32_16x16x32_bf16(Bt[n][k], At[m][k], acc[ai][bj][m][n], 0, 0, 0); __builtin_amdgcn_s_setprio(0); } while (0)
; #define PG8_WAIT_V(n) asm volatile("s_waitcnt vmcnt(" #n ")" ::: "memory")
; #define PG8_WAIT_L(n) asm volatile("s_waitcnt lgkmcnt(" #n ")" ::: "memory")
; #define PG8_BAR __builtin_amdgcn_s_barrier()
; #define PG8_SCHED __builtin_amdgcn_sched_barrier(0)
; template <class Epi, class Sched, bool ALIGN_EPI = false, bool SP2 = false>
; __device__ __forceinline__ void gemm_phase(PG8_LAS unsigned char* lds, const Gemm g, const Sched& S, const Epi& E) {
;     ...
;             const char* a2 = last ? nA : cA + (size_t)(t + 2) * kstep; const char* b2 = last ? nB : cB + (size_t)(t + 2) * kstep;
;             const char* a3 = a2 + kstep; const char* b3 = b2 + kstep;
;             if (last && has_next) S.a_ready(nxt);
;             if constexpr (SP2) {
;             PG8_LDB(B0, 0, 0); PG8_LDB(B1, 0, 1); PG8_SCHED; PG8_LDA(At, 0, 0); PG8_STAGE(PG8_SA(1, 1), a1 + hstep, voffA);
;             PG8_WAIT_V(8); PG8_WAIT_L(0); PG8_BAR; PG8_MMA(0, 0, At, B0); PG8_MMA(0, 1, At, B1); PG8_BAR; PG8_SCHED;
;             PG8_LDA(At, 0, 1); PG8_STAGE(PG8_SB(0, 0), b2, voffB); PG8_STAGE(PG8_SB(0, 1), b2 + hstep, voffB); PG8_STAGE(PG8_SA(0, 0), a2, voffA);
;             PG8_WAIT_V(8); PG8_WAIT_L(0); PG8_BAR; PG8_MMA(1, 0, At, B0); PG8_MMA(1, 1, At, B1); PG8_BAR; PG8_SCHED;
.LBB11_1896:
	s_add_i32 s56, s22, 2
	s_add_u32 s57, s16, s20
	s_addc_u32 s23, s17, s21
	s_add_u32 s58, s14, s20
	s_addc_u32 s59, s15, s21
	s_add_i32 s60, 0, 0x10000
	s_cmp_eq_u32 s49, s22
	s_cselect_b32 s23, s5, s23
	s_cselect_b32 s22, s4, s57
	s_cselect_b32 s59, s19, s59
	s_cselect_b32 s58, s18, s58
	s_add_i32 s57, 0, 0x14000
	v_add_u32_e32 v156, s60, v1
	v_add_u32_e32 v174, s57, v1
	ds_read_b128 v[144:147], v156
	ds_read_b128 v[148:151], v156 offset:1024
	ds_read_b128 v[152:155], v156 offset:2048
	ds_read_b128 v[156:159], v156 offset:3072
	ds_read_b128 v[160:163], v174
	ds_read_b128 v[166:169], v174 offset:1024
	ds_read_b128 v[170:173], v174 offset:2048
	ds_read_b128 v[174:177], v174 offset:3072
	v_lshl_add_u64 v[184:185], s[16:17], 0, v[140:141]
	s_add_i32 m0, s45, 0xc000
	ds_read_b128 v[178:181], v143
	ds_read_b128 v[198:201], v143 offset:1024
	ds_read_b128 v[202:205], v143 offset:2048
	ds_read_b128 v[220:223], v143 offset:3072
	ds_read_b128 v[224:227], v143 offset:4096
	ds_read_b128 v[228:231], v143 offset:5120
	ds_read_b128 v[232:235], v143 offset:6144
	ds_read_b128 v[236:239], v143 offset:7168
	global_load_lds_dwordx4 v[184:185], off
	v_lshl_add_u64 v[184:185], s[16:17], 0, v[138:139]
	s_add_i32 m0, s45, 0xe000
	s_nop 0
	global_load_lds_dwordx4 v[184:185], off
	s_waitcnt vmcnt(8)
	s_waitcnt lgkmcnt(0)
	s_barrier
	s_setprio 1
	s_waitcnt lgkmcnt(0)
	v_mfma_f32_16x16x32_bf16 v[100:103], v[144:147], v[178:181], v[100:103]
	v_mfma_f32_16x16x32_bf16 v[100:103], v[148:151], v[198:201], v[100:103]
	v_mfma_f32_16x16x32_bf16 v[116:119], v[144:147], v[202:205], v[116:119]
	v_mfma_f32_16x16x32_bf16 v[116:119], v[148:151], v[220:223], v[116:119]
	v_mfma_f32_16x16x32_bf16 v[124:127], v[144:147], v[224:227], v[124:127]
	v_mfma_f32_16x16x32_bf16 v[124:127], v[148:151], v[228:231], v[124:127]
	v_mfma_f32_16x16x32_bf16 v[128:131], v[144:147], v[232:235], v[128:131]
	v_mfma_f32_16x16x32_bf16 v[128:131], v[148:151], v[236:239], v[128:131]
	v_mfma_f32_16x16x32_bf16 v[68:71], v[152:155], v[178:181], v[68:71]
	v_mfma_f32_16x16x32_bf16 v[68:71], v[156:159], v[198:201], v[68:71]
	v_mfma_f32_16x16x32_bf16 v[80:83], v[152:155], v[202:205], v[80:83]
	v_mfma_f32_16x16x32_bf16 v[80:83], v[156:159], v[220:223], v[80:83]
	v_mfma_f32_16x16x32_bf16 v[104:107], v[152:155], v[224:227], v[104:107]
	v_mfma_f32_16x16x32_bf16 v[104:107], v[156:159], v[228:231], v[104:107]
	v_mfma_f32_16x16x32_bf16 v[120:123], v[152:155], v[232:235], v[120:123]
	v_mfma_f32_16x16x32_bf16 v[120:123], v[156:159], v[236:239], v[120:123]
	s_setprio 0
	s_setprio 1
	v_mfma_f32_16x16x32_bf16 v[16:19], v[160:163], v[178:181], v[16:19]
	v_mfma_f32_16x16x32_bf16 v[16:19], v[166:169], v[198:201], v[16:19]
	v_mfma_f32_16x16x32_bf16 v[32:35], v[160:163], v[202:205], v[32:35]
	v_mfma_f32_16x16x32_bf16 v[32:35], v[166:169], v[220:223], v[32:35]
	v_mfma_f32_16x16x32_bf16 v[48:51], v[160:163], v[224:227], v[48:51]
	v_mfma_f32_16x16x32_bf16 v[48:51], v[166:169], v[228:231], v[48:51]
	v_mfma_f32_16x16x32_bf16 v[76:79], v[160:163], v[232:235], v[76:79]
	v_mfma_f32_16x16x32_bf16 v[76:79], v[166:169], v[236:239], v[76:79]
	v_mfma_f32_16x16x32_bf16 v[4:7], v[170:173], v[178:181], v[4:7]
	v_mfma_f32_16x16x32_bf16 v[4:7], v[174:177], v[198:201], v[4:7]
	v_mfma_f32_16x16x32_bf16 v[8:11], v[170:173], v[202:205], v[8:11]
	v_mfma_f32_16x16x32_bf16 v[8:11], v[174:177], v[220:223], v[8:11]
	v_mfma_f32_16x16x32_bf16 v[12:15], v[170:173], v[224:227], v[12:15]
	v_mfma_f32_16x16x32_bf16 v[12:15], v[174:177], v[228:231], v[12:15]
	v_mfma_f32_16x16x32_bf16 v[24:27], v[170:173], v[232:235], v[24:27]
	v_mfma_f32_16x16x32_bf16 v[24:27], v[174:177], v[236:239], v[24:27]
	s_setprio 0
	s_barrier
	s_add_i32 s60, s60, s13
	v_lshl_add_u64 v[184:185], s[58:59], 0, v[2:3]
	s_mov_b32 m0, s60
	ds_read_b128 v[178:181], v143 offset:16384
	ds_read_b128 v[198:201], v143 offset:17408
	ds_read_b128 v[202:205], v143 offset:18432
	ds_read_b128 v[220:223], v143 offset:19456
	ds_read_b128 v[224:227], v143 offset:20480
	ds_read_b128 v[228:231], v143 offset:21504
	ds_read_b128 v[232:235], v143 offset:22528
	ds_read_b128 v[236:239], v143 offset:23552
	global_load_lds_dwordx4 v[184:185], off
	s_add_i32 m0, s60, 0x2000
	v_lshl_add_u64 v[186:187], s[58:59], 0, v[132:133]
	s_add_u32 s58, s58, s33
	s_addc_u32 s59, s59, 0
	s_add_i32 s57, s57, s13
	global_load_lds_dwordx4 v[186:187], off
	v_lshl_add_u64 v[196:197], s[58:59], 0, v[2:3]
	s_mov_b32 m0, s57
	v_lshl_add_u64 v[206:207], s[58:59], 0, v[132:133]
	global_load_lds_dwordx4 v[196:197], off
	s_add_i32 m0, s57, 0x2000
	v_lshl_add_u64 v[240:241], s[22:23], 0, v[2:3]
	global_load_lds_dwordx4 v[206:207], off
	s_mov_b32 m0, s45
	v_lshl_add_u64 v[242:243], s[22:23], 0, v[132:133]
	global_load_lds_dwordx4 v[240:241], off
	s_mov_b32 m0, s46
	s_nop 0
	global_load_lds_dwordx4 v[242:243], off
	s_waitcnt vmcnt(8)
	s_waitcnt lgkmcnt(0)
	s_barrier
; #define PG8_STAGE(bufoff, gbase, voff) do { _Pragma("unroll") for (int _i = 0; _i < 2; ++_i) \
;         __builtin_amdgcn_global_load_lds((const unsigned*)((const char*)(gbase) + (voff)[_i]), (PG8_LAS unsigned*)(lds + (bufoff) + ldsw + _i * 8192), 16, 0, 0); } while (0)
; #define PG8_LDA(dst, b, h) do { _Pragma("unroll") for (int m = 0; m < 4; ++m) _Pragma("unroll") for (int k = 0; k < 2; ++k) dst[m][k] = *(const PG8_LAS bf16x8*)(lds + PG8_SA(b, h) + aoff + m * 2048 + k * 1024); } while (0)
; #define PG8_LDB(dst, b, h) do { _Pragma("unroll") for (int n = 0; n < 2; ++n) _Pragma("unroll") for (int k = 0; k < 2; ++k) dst[n][k] = *(const PG8_LAS bf16x8*)(lds + PG8_SB(b, h) + boff + n * 2048 + k * 1024); } while (0)
; #define PG8_MMA(ai, bj, At, Bt) do { __builtin_amdgcn_s_setprio(1); _Pragma("unroll") for (int m = 0; m < 4; ++m) _Pragma("unroll") for (int n = 0; n < 2; ++n) _Pragma("unroll") for (int k = 0; k < 2; ++k) \
;         acc[ai][bj][m][n] = __builtin_amdgcn_mfma_f32_16x16x32_bf16(Bt[n][k], At[m][k], acc[ai][bj][m][n], 0, 0, 0); __builtin_amdgcn_s_setprio(0); } while (0)
; #define PG8_WAIT_V(n) asm volatile("s_waitcnt vmcnt(" #n ")" ::: "memory")
; #define PG8_WAIT_L(n) asm volatile("s_waitcnt lgkmcnt(" #n ")" ::: "memory")
; #define PG8_BAR __builtin_amdgcn_s_barrier()
; #define PG8_SCHED __builtin_amdgcn_sched_barrier(0)
; template <class Epi, class Sched, bool ALIGN_EPI = false, bool SP2 = false>
; __device__ __forceinline__ void gemm_phase(PG8_LAS unsigned char* lds, const Gemm g, const Sched& S, const Epi& E) {
;     ...
;             PG8_WAIT_V(8); PG8_WAIT_L(0); PG8_BAR; PG8_MMA(1, 0, At, B0); PG8_MMA(1, 1, At, B1); PG8_BAR; PG8_SCHED;
;             PG8_LDB(B0, 1, 0); PG8_LDB(B1, 1, 1); PG8_SCHED; PG8_LDA(At, 1, 0); PG8_STAGE(PG8_SA(0, 1), a2 + hstep, voffA);
;             PG8_WAIT_V(8); PG8_WAIT_L(0); PG8_BAR; PG8_MMA(0, 0, At, B0); PG8_MMA(0, 1, At, B1); PG8_BAR; PG8_SCHED;
;             PG8_LDA(At, 1, 1); PG8_STAGE(PG8_SB(1, 0), b3, voffB); PG8_STAGE(PG8_SB(1, 1), b3 + hstep, voffB); PG8_STAGE(PG8_SA(1, 0), a3, voffA);
	s_setprio 1
	s_waitcnt lgkmcnt(0)
	v_mfma_f32_16x16x32_bf16 v[108:111], v[144:147], v[178:181], v[108:111]
	v_mfma_f32_16x16x32_bf16 v[108:111], v[148:151], v[198:201], v[108:111]
	v_mfma_f32_16x16x32_bf16 v[88:91], v[144:147], v[202:205], v[88:91]
	v_mfma_f32_16x16x32_bf16 v[88:91], v[148:151], v[220:223], v[88:91]
	v_mfma_f32_16x16x32_bf16 v[60:63], v[144:147], v[224:227], v[60:63]
	v_mfma_f32_16x16x32_bf16 v[60:63], v[148:151], v[228:231], v[60:63]
	v_mfma_f32_16x16x32_bf16 v[36:39], v[144:147], v[232:235], v[36:39]
	v_mfma_f32_16x16x32_bf16 v[36:39], v[148:151], v[236:239], v[36:39]
	v_mfma_f32_16x16x32_bf16 v[112:115], v[152:155], v[178:181], v[112:115]
	v_mfma_f32_16x16x32_bf16 v[112:115], v[156:159], v[198:201], v[112:115]
	v_mfma_f32_16x16x32_bf16 v[92:95], v[152:155], v[202:205], v[92:95]
	v_mfma_f32_16x16x32_bf16 v[92:95], v[156:159], v[220:223], v[92:95]
	v_mfma_f32_16x16x32_bf16 v[64:67], v[152:155], v[224:227], v[64:67]
	v_mfma_f32_16x16x32_bf16 v[64:67], v[156:159], v[228:231], v[64:67]
	v_mfma_f32_16x16x32_bf16 v[40:43], v[152:155], v[232:235], v[40:43]
	v_mfma_f32_16x16x32_bf16 v[40:43], v[156:159], v[236:239], v[40:43]
	s_setprio 0
	s_setprio 1
	v_mfma_f32_16x16x32_bf16 v[96:99], v[160:163], v[178:181], v[96:99]
	v_mfma_f32_16x16x32_bf16 v[96:99], v[166:169], v[198:201], v[96:99]
	v_mfma_f32_16x16x32_bf16 v[84:87], v[160:163], v[202:205], v[84:87]
	v_mfma_f32_16x16x32_bf16 v[84:87], v[166:169], v[220:223], v[84:87]
	v_mfma_f32_16x16x32_bf16 v[56:59], v[160:163], v[224:227], v[56:59]
	v_mfma_f32_16x16x32_bf16 v[56:59], v[166:169], v[228:231], v[56:59]
	v_mfma_f32_16x16x32_bf16 v[28:31], v[160:163], v[232:235], v[28:31]
	v_mfma_f32_16x16x32_bf16 v[28:31], v[166:169], v[236:239], v[28:31]
	v_mfma_f32_16x16x32_bf16 v[44:47], v[170:173], v[178:181], v[44:47]
	v_mfma_f32_16x16x32_bf16 v[44:47], v[174:177], v[198:201], v[44:47]
	v_mfma_f32_16x16x32_bf16 v[72:75], v[170:173], v[202:205], v[72:75]
	v_mfma_f32_16x16x32_bf16 v[72:75], v[174:177], v[220:223], v[72:75]
	v_mfma_f32_16x16x32_bf16 v[52:55], v[170:173], v[224:227], v[52:55]
	v_mfma_f32_16x16x32_bf16 v[52:55], v[174:177], v[228:231], v[52:55]
	v_mfma_f32_16x16x32_bf16 v[20:23], v[170:173], v[232:235], v[20:23]
	v_mfma_f32_16x16x32_bf16 v[20:23], v[174:177], v[236:239], v[20:23]
	s_setprio 0
	s_barrier
	s_add_i32 s57, 0, 0x18000
	s_add_i32 s58, 0, 0x1c000
	v_add_u32_e32 v156, s57, v1
	v_add_u32_e32 v174, s58, v1
	ds_read_b128 v[144:147], v156
	ds_read_b128 v[148:151], v156 offset:1024
	ds_read_b128 v[152:155], v156 offset:2048
	ds_read_b128 v[156:159], v156 offset:3072
	ds_read_b128 v[160:163], v174
	ds_read_b128 v[166:169], v174 offset:1024
	ds_read_b128 v[170:173], v174 offset:2048
	ds_read_b128 v[174:177], v174 offset:3072
	s_add_u32 s22, s22, s33
	s_addc_u32 s23, s23, 0
	s_mov_b32 m0, s47
	v_lshl_add_u64 v[244:245], s[22:23], 0, v[2:3]
	ds_read_b128 v[178:181], v143 offset:32768
	ds_read_b128 v[198:201], v143 offset:33792
	ds_read_b128 v[202:205], v143 offset:34816
	ds_read_b128 v[220:223], v143 offset:35840
	ds_read_b128 v[224:227], v143 offset:36864
	ds_read_b128 v[228:231], v143 offset:37888
	ds_read_b128 v[232:235], v143 offset:38912
	ds_read_b128 v[236:239], v143 offset:39936
	global_load_lds_dwordx4 v[244:245], off
	v_lshl_add_u64 v[244:245], s[22:23], 0, v[132:133]
	s_mov_b32 m0, s48
	s_nop 0
	global_load_lds_dwordx4 v[244:245], off
	s_waitcnt vmcnt(8)
	s_waitcnt lgkmcnt(0)
	s_barrier
	s_setprio 1
	s_waitcnt lgkmcnt(0)
	v_mfma_f32_16x16x32_bf16 v[100:103], v[144:147], v[178:181], v[100:103]
	v_mfma_f32_16x16x32_bf16 v[100:103], v[148:151], v[198:201], v[100:103]
	v_mfma_f32_16x16x32_bf16 v[116:119], v[144:147], v[202:205], v[116:119]
	v_mfma_f32_16x16x32_bf16 v[116:119], v[148:151], v[220:223], v[116:119]
	v_mfma_f32_16x16x32_bf16 v[124:127], v[144:147], v[224:227], v[124:127]
	v_mfma_f32_16x16x32_bf16 v[124:127], v[148:151], v[228:231], v[124:127]
	v_mfma_f32_16x16x32_bf16 v[128:131], v[144:147], v[232:235], v[128:131]
	v_mfma_f32_16x16x32_bf16 v[128:131], v[148:151], v[236:239], v[128:131]
	v_mfma_f32_16x16x32_bf16 v[68:71], v[152:155], v[178:181], v[68:71]
	v_mfma_f32_16x16x32_bf16 v[68:71], v[156:159], v[198:201], v[68:71]
	v_mfma_f32_16x16x32_bf16 v[80:83], v[152:155], v[202:205], v[80:83]
	v_mfma_f32_16x16x32_bf16 v[80:83], v[156:159], v[220:223], v[80:83]
	v_mfma_f32_16x16x32_bf16 v[104:107], v[152:155], v[224:227], v[104:107]
	v_mfma_f32_16x16x32_bf16 v[104:107], v[156:159], v[228:231], v[104:107]
	v_mfma_f32_16x16x32_bf16 v[120:123], v[152:155], v[232:235], v[120:123]
	v_mfma_f32_16x16x32_bf16 v[120:123], v[156:159], v[236:239], v[120:123]
	s_setprio 0
	s_setprio 1
	v_mfma_f32_16x16x32_bf16 v[16:19], v[160:163], v[178:181], v[16:19]
	v_mfma_f32_16x16x32_bf16 v[16:19], v[166:169], v[198:201], v[16:19]
	v_mfma_f32_16x16x32_bf16 v[32:35], v[160:163], v[202:205], v[32:35]
	v_mfma_f32_16x16x32_bf16 v[32:35], v[166:169], v[220:223], v[32:35]
	v_mfma_f32_16x16x32_bf16 v[48:51], v[160:163], v[224:227], v[48:51]
	v_mfma_f32_16x16x32_bf16 v[48:51], v[166:169], v[228:231], v[48:51]
	v_mfma_f32_16x16x32_bf16 v[76:79], v[160:163], v[232:235], v[76:79]
	v_mfma_f32_16x16x32_bf16 v[76:79], v[166:169], v[236:239], v[76:79]
	v_mfma_f32_16x16x32_bf16 v[4:7], v[170:173], v[178:181], v[4:7]
	v_mfma_f32_16x16x32_bf16 v[4:7], v[174:177], v[198:201], v[4:7]
	v_mfma_f32_16x16x32_bf16 v[8:11], v[170:173], v[202:205], v[8:11]
	v_mfma_f32_16x16x32_bf16 v[8:11], v[174:177], v[220:223], v[8:11]
	v_mfma_f32_16x16x32_bf16 v[12:15], v[170:173], v[224:227], v[12:15]
	v_mfma_f32_16x16x32_bf16 v[12:15], v[174:177], v[228:231], v[12:15]
	v_mfma_f32_16x16x32_bf16 v[24:27], v[170:173], v[232:235], v[24:27]
	v_mfma_f32_16x16x32_bf16 v[24:27], v[174:177], v[236:239], v[24:27]
	s_setprio 0
	s_barrier
; #define PG8_STAGE(bufoff, gbase, voff) do { _Pragma("unroll") for (int _i = 0; _i < 2; ++_i) \
;         __builtin_amdgcn_global_load_lds((const unsigned*)((const char*)(gbase) + (voff)[_i]), (PG8_LAS unsigned*)(lds + (bufoff) + ldsw + _i * 8192), 16, 0, 0); } while (0)
; #define PG8_LDA(dst, b, h) do { _Pragma("unroll") for (int m = 0; m < 4; ++m) _Pragma("unroll") for (int k = 0; k < 2; ++k) dst[m][k] = *(const PG8_LAS bf16x8*)(lds + PG8_SA(b, h) + aoff + m * 2048 + k * 1024); } while (0)
; #define PG8_MMA(ai, bj, At, Bt) do { __builtin_amdgcn_s_setprio(1); _Pragma("unroll") for (int m = 0; m < 4; ++m) _Pragma("unroll") for (int n = 0; n < 2; ++n) _Pragma("unroll") for (int k = 0; k < 2; ++k) \
;         acc[ai][bj][m][n] = __builtin_amdgcn_mfma_f32_16x16x32_bf16(Bt[n][k], At[m][k], acc[ai][bj][m][n], 0, 0, 0); __builtin_amdgcn_s_setprio(0); } while (0)
; #define PG8_WAIT_V(n) asm volatile("s_waitcnt vmcnt(" #n ")" ::: "memory")
; #define PG8_WAIT_L(n) asm volatile("s_waitcnt lgkmcnt(" #n ")" ::: "memory")
; #define PG8_BAR __builtin_amdgcn_s_barrier()
; #define PG8_SCHED __builtin_amdgcn_sched_barrier(0)
; template <class Epi, class Sched, bool ALIGN_EPI = false, bool SP2 = false>
; __device__ __forceinline__ void gemm_phase(PG8_LAS unsigned char* lds, const Gemm g, const Sched& S, const Epi& E) {
;     ...
;             PG8_LDA(At, 1, 1); PG8_STAGE(PG8_SB(1, 0), b3, voffB); PG8_STAGE(PG8_SB(1, 1), b3 + hstep, voffB); PG8_STAGE(PG8_SA(1, 0), a3, voffA);
;             PG8_WAIT_V(8); PG8_WAIT_L(0); PG8_BAR; PG8_MMA(1, 0, At, B0); PG8_MMA(1, 1, At, B1); PG8_BAR; PG8_SCHED;
;     ...
;         if (!has_next) break;
; #pragma unroll
;         for (int a = 0; a < 2; ++a)
; #pragma unroll
;             for (int b = 0; b < 2; ++b)
; #pragma unroll
;                 for (int m = 0; m < 4; ++m)
; #pragma unroll
;                     for (int n = 0; n < 2; ++n) acc[a][b][m][n] = (f32x4){0.f, 0.f, 0.f, 0.f};
;         cur = nxt; cA = nA; cB = nB; ++ui;
	s_add_i32 s22, s57, s13
	v_lshl_add_u64 v[184:185], v[184:185], 0, s[34:35]
	s_mov_b32 m0, s22
	ds_read_b128 v[178:181], v143 offset:49152
	ds_read_b128 v[198:201], v143 offset:50176
	ds_read_b128 v[202:205], v143 offset:51200
	ds_read_b128 v[220:223], v143 offset:52224
	ds_read_b128 v[224:227], v143 offset:53248
	ds_read_b128 v[228:231], v143 offset:54272
	ds_read_b128 v[232:235], v143 offset:55296
	ds_read_b128 v[236:239], v143 offset:56320
	global_load_lds_dwordx4 v[184:185], off
	v_lshl_add_u64 v[184:185], v[186:187], 0, s[34:35]
	s_add_i32 m0, s22, 0x2000
	s_add_i32 s22, s58, s13
	global_load_lds_dwordx4 v[184:185], off
	v_lshl_add_u64 v[184:185], v[196:197], 0, s[34:35]
	s_mov_b32 m0, s22
	s_nop 0
	global_load_lds_dwordx4 v[184:185], off
	v_lshl_add_u64 v[184:185], v[206:207], 0, s[34:35]
	s_add_i32 m0, s22, 0x2000
	s_nop 0
	global_load_lds_dwordx4 v[184:185], off
	v_lshl_add_u64 v[184:185], v[240:241], 0, s[34:35]
	s_mov_b32 m0, s50
	s_nop 0
	global_load_lds_dwordx4 v[184:185], off
	v_lshl_add_u64 v[184:185], v[242:243], 0, s[34:35]
	s_mov_b32 m0, s51
	s_nop 0
	global_load_lds_dwordx4 v[184:185], off
	s_waitcnt vmcnt(8)
	s_waitcnt lgkmcnt(0)
	s_barrier
	s_setprio 1
	s_waitcnt lgkmcnt(0)
	v_mfma_f32_16x16x32_bf16 v[108:111], v[144:147], v[178:181], v[108:111]
	v_mfma_f32_16x16x32_bf16 v[108:111], v[148:151], v[198:201], v[108:111]
	v_mfma_f32_16x16x32_bf16 v[88:91], v[144:147], v[202:205], v[88:91]
	v_mfma_f32_16x16x32_bf16 v[88:91], v[148:151], v[220:223], v[88:91]
	v_mfma_f32_16x16x32_bf16 v[60:63], v[144:147], v[224:227], v[60:63]
	v_mfma_f32_16x16x32_bf16 v[60:63], v[148:151], v[228:231], v[60:63]
	v_mfma_f32_16x16x32_bf16 v[36:39], v[144:147], v[232:235], v[36:39]
	v_mfma_f32_16x16x32_bf16 v[36:39], v[148:151], v[236:239], v[36:39]
	v_mfma_f32_16x16x32_bf16 v[112:115], v[152:155], v[178:181], v[112:115]
	v_mfma_f32_16x16x32_bf16 v[112:115], v[156:159], v[198:201], v[112:115]
	v_mfma_f32_16x16x32_bf16 v[92:95], v[152:155], v[202:205], v[92:95]
	v_mfma_f32_16x16x32_bf16 v[92:95], v[156:159], v[220:223], v[92:95]
	v_mfma_f32_16x16x32_bf16 v[64:67], v[152:155], v[224:227], v[64:67]
	v_mfma_f32_16x16x32_bf16 v[64:67], v[156:159], v[228:231], v[64:67]
	v_mfma_f32_16x16x32_bf16 v[40:43], v[152:155], v[232:235], v[40:43]
	v_mfma_f32_16x16x32_bf16 v[40:43], v[156:159], v[236:239], v[40:43]
	s_setprio 0
	s_setprio 1
	v_mfma_f32_16x16x32_bf16 v[96:99], v[160:163], v[178:181], v[96:99]
	v_mfma_f32_16x16x32_bf16 v[96:99], v[166:169], v[198:201], v[96:99]
	v_mfma_f32_16x16x32_bf16 v[84:87], v[160:163], v[202:205], v[84:87]
	v_mfma_f32_16x16x32_bf16 v[84:87], v[166:169], v[220:223], v[84:87]
	v_mfma_f32_16x16x32_bf16 v[56:59], v[160:163], v[224:227], v[56:59]
	v_mfma_f32_16x16x32_bf16 v[56:59], v[166:169], v[228:231], v[56:59]
	v_mfma_f32_16x16x32_bf16 v[28:31], v[160:163], v[232:235], v[28:31]
	v_mfma_f32_16x16x32_bf16 v[28:31], v[166:169], v[236:239], v[28:31]
	v_mfma_f32_16x16x32_bf16 v[44:47], v[170:173], v[178:181], v[44:47]
	v_mfma_f32_16x16x32_bf16 v[44:47], v[174:177], v[198:201], v[44:47]
	v_mfma_f32_16x16x32_bf16 v[72:75], v[170:173], v[202:205], v[72:75]
	v_mfma_f32_16x16x32_bf16 v[72:75], v[174:177], v[220:223], v[72:75]
	v_mfma_f32_16x16x32_bf16 v[52:55], v[170:173], v[224:227], v[52:55]
	v_mfma_f32_16x16x32_bf16 v[52:55], v[174:177], v[228:231], v[52:55]
	v_mfma_f32_16x16x32_bf16 v[20:23], v[170:173], v[232:235], v[20:23]
	v_mfma_f32_16x16x32_bf16 v[20:23], v[174:177], v[236:239], v[20:23]
	s_setprio 0
	s_barrier
	s_add_u32 s20, s20, 0x100
	s_addc_u32 s21, s21, 0
	v_lshl_add_u64 v[140:141], v[140:141], 0, s[62:63]
	v_lshl_add_u64 v[138:139], v[138:139], 0, s[62:63]
	s_cmp_ge_u32 s56, s29
	s_mov_b32 s22, s56
	s_cbranch_scc0 .LBB11_1896
	s_and_b64 vcc, exec, s[38:39]
	s_cbranch_vccnz .LBB11_1884
	v_mov_b32_e32 v20, 0
	s_mov_b32 s42, s53
	s_mov_b32 s28, s54
	s_mov_b64 s[14:15], s[18:19]
	s_mov_b64 s[16:17], s[4:5]
	s_mov_b32 s52, s55
	v_mov_b32_e32 v21, v20
	v_mov_b32_e32 v22, v20
	v_mov_b32_e32 v23, v20
	v_mov_b32_e32 v28, v20
	v_mov_b32_e32 v29, v20
	v_mov_b32_e32 v30, v20
	v_mov_b32_e32 v31, v20
	v_mov_b32_e32 v52, v20
	v_mov_b32_e32 v53, v20
	v_mov_b32_e32 v54, v20
	v_mov_b32_e32 v55, v20
	v_mov_b32_e32 v56, v20
	v_mov_b32_e32 v57, v20
	v_mov_b32_e32 v58, v20
	v_mov_b32_e32 v59, v20
	v_mov_b32_e32 v72, v20
	v_mov_b32_e32 v73, v20
	v_mov_b32_e32 v74, v20
	v_mov_b32_e32 v75, v20
	v_mov_b32_e32 v84, v20
	v_mov_b32_e32 v85, v20
	v_mov_b32_e32 v86, v20
	v_mov_b32_e32 v87, v20
	v_mov_b32_e32 v44, v20
	v_mov_b32_e32 v45, v20
	v_mov_b32_e32 v46, v20
	v_mov_b32_e32 v47, v20
	v_mov_b32_e32 v96, v20
	v_mov_b32_e32 v97, v20
	v_mov_b32_e32 v98, v20
	v_mov_b32_e32 v99, v20
	v_mov_b32_e32 v40, v20
	v_mov_b32_e32 v41, v20
	v_mov_b32_e32 v42, v20
	v_mov_b32_e32 v43, v20
	v_mov_b32_e32 v36, v20
	v_mov_b32_e32 v37, v20
	v_mov_b32_e32 v38, v20
	v_mov_b32_e32 v39, v20
	v_mov_b32_e32 v64, v20
	v_mov_b32_e32 v65, v20
	v_mov_b32_e32 v66, v20
	v_mov_b32_e32 v67, v20
	v_mov_b32_e32 v60, v20
	v_mov_b32_e32 v61, v20
	v_mov_b32_e32 v62, v20
	v_mov_b32_e32 v63, v20
	v_mov_b32_e32 v92, v20
	v_mov_b32_e32 v93, v20
	v_mov_b32_e32 v94, v20
	v_mov_b32_e32 v95, v20
	v_mov_b32_e32 v88, v20
	v_mov_b32_e32 v89, v20
	v_mov_b32_e32 v90, v20
	v_mov_b32_e32 v91, v20
	v_mov_b32_e32 v112, v20
	v_mov_b32_e32 v113, v20
	v_mov_b32_e32 v114, v20
	v_mov_b32_e32 v115, v20
	v_mov_b32_e32 v108, v20
	v_mov_b32_e32 v109, v20
	v_mov_b32_e32 v110, v20
	v_mov_b32_e32 v111, v20
	v_mov_b32_e32 v24, v20
	v_mov_b32_e32 v25, v20
	v_mov_b32_e32 v26, v20
	v_mov_b32_e32 v27, v20
	v_mov_b32_e32 v76, v20
	v_mov_b32_e32 v77, v20
	v_mov_b32_e32 v78, v20
	v_mov_b32_e32 v79, v20
	v_mov_b32_e32 v12, v20
	v_mov_b32_e32 v13, v20
	v_mov_b32_e32 v14, v20
	v_mov_b32_e32 v15, v20
	v_mov_b32_e32 v48, v20
	v_mov_b32_e32 v49, v20
	v_mov_b32_e32 v50, v20
	v_mov_b32_e32 v51, v20
	v_mov_b32_e32 v8, v20
	v_mov_b32_e32 v9, v20
	v_mov_b32_e32 v10, v20
	v_mov_b32_e32 v11, v20
	v_mov_b32_e32 v32, v20
	v_mov_b32_e32 v33, v20
	v_mov_b32_e32 v34, v20
	v_mov_b32_e32 v35, v20
	v_mov_b32_e32 v4, v20
	v_mov_b32_e32 v5, v20
	v_mov_b32_e32 v6, v20
	v_mov_b32_e32 v7, v20
	v_mov_b32_e32 v16, v20
	v_mov_b32_e32 v17, v20
	v_mov_b32_e32 v18, v20
	v_mov_b32_e32 v19, v20
	v_mov_b32_e32 v120, v20
	v_mov_b32_e32 v121, v20
	v_mov_b32_e32 v122, v20
	v_mov_b32_e32 v123, v20
	v_mov_b32_e32 v128, v20
	v_mov_b32_e32 v129, v20
	v_mov_b32_e32 v130, v20
	v_mov_b32_e32 v131, v20
	v_mov_b32_e32 v104, v20
	v_mov_b32_e32 v105, v20
	v_mov_b32_e32 v106, v20
	v_mov_b32_e32 v107, v20
	v_mov_b32_e32 v124, v20
	v_mov_b32_e32 v125, v20
	v_mov_b32_e32 v126, v20
	v_mov_b32_e32 v127, v20
	v_mov_b32_e32 v80, v20
	v_mov_b32_e32 v81, v20
	v_mov_b32_e32 v82, v20
	v_mov_b32_e32 v83, v20
	v_mov_b32_e32 v116, v20
	v_mov_b32_e32 v117, v20
	v_mov_b32_e32 v118, v20
	v_mov_b32_e32 v119, v20
	v_mov_b32_e32 v68, v20
	v_mov_b32_e32 v69, v20
	v_mov_b32_e32 v70, v20
	v_mov_b32_e32 v71, v20
	v_mov_b32_e32 v100, v20
	v_mov_b32_e32 v101, v20
	v_mov_b32_e32 v102, v20
	v_mov_b32_e32 v103, v20
	s_branch .LBB11_1884
